# hand-written residual-GEMM epilogue: v_permlane16_swap pairs accumulator tiles so each lane owns 8 columns (16-byte loads/stores, half the scattered accesses), residual loads up front, atomics at the
# speedup vs baseline: 1.0346x; 1.0067x over previous
.LBB0_1016:
	v_lshl_add_u32 v238, s44, 8, v146
	v_and_b32_e32 v240, 0xe0, v148
	v_and_b32_e32 v241, 4, v148
	v_lshl_or_b32 v240, v241, 2, v240
	v_and_b32_e32 v241, 8, v148
	v_or_b32_e32 v240, v240, v241
	v_lshl_or_b32 v240, s45, 8, v240
	v_mov_b32_e32 v241, 0
	v_ashrrev_i32_e32 v239, 31, v238
	v_readlane_b32 s20, v234, 22
	v_readlane_b32 s21, v234, 23
	v_lshlrev_b64 v[244:245], 11, v[238:239]
	v_lshl_add_u64 v[244:245], v[244:245], 0, v[240:241]
	v_lshl_add_u64 v[144:145], v[244:245], 1, s[20:21]
	s_mov_b32 s101, 0
	global_load_dwordx4 v[140:143], v[144:145], off
	global_load_dwordx4 v[154:157], v[144:145], off offset:256
	s_mov_b32 s100, 0x10000
	v_lshl_add_u64 v[236:237], v[144:145], 0, s[100:101]
	global_load_dwordx4 v[158:161], v[236:237], off
	global_load_dwordx4 v[162:165], v[236:237], off offset:256
	s_mov_b32 s100, 0x20000
	v_lshl_add_u64 v[236:237], v[144:145], 0, s[100:101]
	global_load_dwordx4 v[166:169], v[236:237], off
	global_load_dwordx4 v[170:173], v[236:237], off offset:256
	s_mov_b32 s100, 0x30000
	v_lshl_add_u64 v[236:237], v[144:145], 0, s[100:101]
	global_load_dwordx4 v[174:177], v[236:237], off
	global_load_dwordx4 v[178:181], v[236:237], off offset:256
	s_mov_b32 s100, 0x80000
	v_lshl_add_u64 v[236:237], v[144:145], 0, s[100:101]
	global_load_dwordx4 v[184:187], v[236:237], off
	global_load_dwordx4 v[190:193], v[236:237], off offset:256
	s_mov_b32 s100, 0x90000
	v_lshl_add_u64 v[236:237], v[144:145], 0, s[100:101]
	global_load_dwordx4 v[194:197], v[236:237], off
	global_load_dwordx4 v[198:201], v[236:237], off offset:256
	s_mov_b32 s100, 0xa0000
	v_lshl_add_u64 v[236:237], v[144:145], 0, s[100:101]
	global_load_dwordx4 v[202:205], v[236:237], off
	global_load_dwordx4 v[206:209], v[236:237], off offset:256
	s_mov_b32 s100, 0xb0000
	v_lshl_add_u64 v[236:237], v[144:145], 0, s[100:101]
	global_load_dwordx4 v[210:213], v[236:237], off
	global_load_dwordx4 v[214:217], v[236:237], off offset:256
	v_xor_b32_e32 v153, 16, v152
	v_xor_b32_e32 v242, 32, v152
	v_lshlrev_b32_e32 v153, 2, v153
	v_lshlrev_b32_e32 v242, 2, v242
	v_permlane16_swap_b32_e32 v124, v120
	v_permlane16_swap_b32_e32 v125, v121
	v_permlane16_swap_b32_e32 v126, v122
	v_permlane16_swap_b32_e32 v127, v123
	v_permlane16_swap_b32_e32 v116, v112
	v_permlane16_swap_b32_e32 v117, v113
	v_permlane16_swap_b32_e32 v118, v114
	v_permlane16_swap_b32_e32 v119, v115
	v_permlane16_swap_b32_e32 v108, v104
	v_permlane16_swap_b32_e32 v109, v105
	v_permlane16_swap_b32_e32 v110, v106
	v_permlane16_swap_b32_e32 v111, v107
	v_permlane16_swap_b32_e32 v100, v96
	v_permlane16_swap_b32_e32 v101, v97
	v_permlane16_swap_b32_e32 v102, v98
	v_permlane16_swap_b32_e32 v103, v99
	v_permlane16_swap_b32_e32 v92, v88
	v_permlane16_swap_b32_e32 v93, v89
	v_permlane16_swap_b32_e32 v94, v90
	v_permlane16_swap_b32_e32 v95, v91
	v_permlane16_swap_b32_e32 v84, v80
	v_permlane16_swap_b32_e32 v85, v81
	v_permlane16_swap_b32_e32 v86, v82
	v_permlane16_swap_b32_e32 v87, v83
	v_permlane16_swap_b32_e32 v76, v72
	v_permlane16_swap_b32_e32 v77, v73
	v_permlane16_swap_b32_e32 v78, v74
	v_permlane16_swap_b32_e32 v79, v75
	v_permlane16_swap_b32_e32 v68, v64
	v_permlane16_swap_b32_e32 v69, v65
	v_permlane16_swap_b32_e32 v70, v66
	v_permlane16_swap_b32_e32 v71, v67
	v_permlane16_swap_b32_e32 v60, v56
	v_permlane16_swap_b32_e32 v61, v57
	v_permlane16_swap_b32_e32 v62, v58
	v_permlane16_swap_b32_e32 v63, v59
	v_permlane16_swap_b32_e32 v52, v48
	v_permlane16_swap_b32_e32 v53, v49
	v_permlane16_swap_b32_e32 v54, v50
	v_permlane16_swap_b32_e32 v55, v51
	v_permlane16_swap_b32_e32 v44, v40
	v_permlane16_swap_b32_e32 v45, v41
	v_permlane16_swap_b32_e32 v46, v42
	v_permlane16_swap_b32_e32 v47, v43
	v_permlane16_swap_b32_e32 v36, v32
	v_permlane16_swap_b32_e32 v37, v33
	v_permlane16_swap_b32_e32 v38, v34
	v_permlane16_swap_b32_e32 v39, v35
	v_permlane16_swap_b32_e32 v28, v24
	v_permlane16_swap_b32_e32 v29, v25
	v_permlane16_swap_b32_e32 v30, v26
	v_permlane16_swap_b32_e32 v31, v27
	v_permlane16_swap_b32_e32 v20, v16
	v_permlane16_swap_b32_e32 v21, v17
	v_permlane16_swap_b32_e32 v22, v18
	v_permlane16_swap_b32_e32 v23, v19
	v_permlane16_swap_b32_e32 v12, v8
	v_permlane16_swap_b32_e32 v13, v9
	v_permlane16_swap_b32_e32 v14, v10
	v_permlane16_swap_b32_e32 v15, v11
	v_permlane16_swap_b32_e32 v4, v0
	v_permlane16_swap_b32_e32 v5, v1
	v_permlane16_swap_b32_e32 v6, v2
	v_permlane16_swap_b32_e32 v7, v3
	s_waitcnt vmcnt(14)
	v_lshlrev_b32_e32 v244, 16, v140
	v_and_b32_e32 v245, 0xffff0000, v140
	v_fma_f32 v124, v124, 0.5, v244
	v_fma_f32 v125, v125, 0.5, v245
	v_mul_f32_e32 v243, v124, v124
	v_fmac_f32_e32 v243, v125, v125
	v_cvt_pk_bf16_f32 v140, v124, v125
	v_lshlrev_b32_e32 v244, 16, v141
	v_and_b32_e32 v245, 0xffff0000, v141
	v_fma_f32 v126, v126, 0.5, v244
	v_fma_f32 v127, v127, 0.5, v245
	v_fmac_f32_e32 v243, v126, v126
	v_fmac_f32_e32 v243, v127, v127
	v_cvt_pk_bf16_f32 v141, v126, v127
	v_lshlrev_b32_e32 v244, 16, v142
	v_and_b32_e32 v245, 0xffff0000, v142
	v_fma_f32 v120, v120, 0.5, v244
	v_fma_f32 v121, v121, 0.5, v245
	v_fmac_f32_e32 v243, v120, v120
	v_fmac_f32_e32 v243, v121, v121
	v_cvt_pk_bf16_f32 v142, v120, v121
	v_lshlrev_b32_e32 v244, 16, v143
	v_and_b32_e32 v245, 0xffff0000, v143
	v_fma_f32 v122, v122, 0.5, v244
	v_fma_f32 v123, v123, 0.5, v245
	v_fmac_f32_e32 v243, v122, v122
	v_fmac_f32_e32 v243, v123, v123
	v_cvt_pk_bf16_f32 v143, v122, v123
	global_store_dwordx4 v[144:145], v[140:143], off
	v_lshlrev_b32_e32 v244, 16, v154
	v_and_b32_e32 v245, 0xffff0000, v154
	v_fma_f32 v116, v116, 0.5, v244
	v_fma_f32 v117, v117, 0.5, v245
	v_fmac_f32_e32 v243, v116, v116
	v_fmac_f32_e32 v243, v117, v117
	v_cvt_pk_bf16_f32 v154, v116, v117
	v_lshlrev_b32_e32 v244, 16, v155
	v_and_b32_e32 v245, 0xffff0000, v155
	v_fma_f32 v118, v118, 0.5, v244
	v_fma_f32 v119, v119, 0.5, v245
	v_fmac_f32_e32 v243, v118, v118
	v_fmac_f32_e32 v243, v119, v119
	v_cvt_pk_bf16_f32 v155, v118, v119
	v_lshlrev_b32_e32 v244, 16, v156
	v_and_b32_e32 v245, 0xffff0000, v156
	v_fma_f32 v112, v112, 0.5, v244
	v_fma_f32 v113, v113, 0.5, v245
	v_fmac_f32_e32 v243, v112, v112
	v_fmac_f32_e32 v243, v113, v113
	v_cvt_pk_bf16_f32 v156, v112, v113
	v_lshlrev_b32_e32 v244, 16, v157
	v_and_b32_e32 v245, 0xffff0000, v157
	v_fma_f32 v114, v114, 0.5, v244
	v_fma_f32 v115, v115, 0.5, v245
	v_fmac_f32_e32 v243, v114, v114
	v_fmac_f32_e32 v243, v115, v115
	v_cvt_pk_bf16_f32 v157, v114, v115
	global_store_dwordx4 v[144:145], v[154:157], off offset:256
	s_waitcnt vmcnt(14)
	s_mov_b32 s100, 0x10000
	v_lshl_add_u64 v[236:237], v[144:145], 0, s[100:101]
	v_lshlrev_b32_e32 v244, 16, v158
	v_and_b32_e32 v245, 0xffff0000, v158
	v_fma_f32 v108, v108, 0.5, v244
	v_fma_f32 v109, v109, 0.5, v245
	v_mul_f32_e32 v124, v108, v108
	v_fmac_f32_e32 v124, v109, v109
	v_cvt_pk_bf16_f32 v158, v108, v109
	v_lshlrev_b32_e32 v244, 16, v159
	v_and_b32_e32 v245, 0xffff0000, v159
	v_fma_f32 v110, v110, 0.5, v244
	v_fma_f32 v111, v111, 0.5, v245
	v_fmac_f32_e32 v124, v110, v110
	v_fmac_f32_e32 v124, v111, v111
	v_cvt_pk_bf16_f32 v159, v110, v111
	v_lshlrev_b32_e32 v244, 16, v160
	v_and_b32_e32 v245, 0xffff0000, v160
	v_fma_f32 v104, v104, 0.5, v244
	v_fma_f32 v105, v105, 0.5, v245
	v_fmac_f32_e32 v124, v104, v104
	v_fmac_f32_e32 v124, v105, v105
	v_cvt_pk_bf16_f32 v160, v104, v105
	v_lshlrev_b32_e32 v244, 16, v161
	v_and_b32_e32 v245, 0xffff0000, v161
	v_fma_f32 v106, v106, 0.5, v244
	v_fma_f32 v107, v107, 0.5, v245
	v_fmac_f32_e32 v124, v106, v106
	v_fmac_f32_e32 v124, v107, v107
	v_cvt_pk_bf16_f32 v161, v106, v107
	global_store_dwordx4 v[236:237], v[158:161], off
	v_lshlrev_b32_e32 v244, 16, v162
	v_and_b32_e32 v245, 0xffff0000, v162
	v_fma_f32 v100, v100, 0.5, v244
	v_fma_f32 v101, v101, 0.5, v245
	v_fmac_f32_e32 v124, v100, v100
	v_fmac_f32_e32 v124, v101, v101
	v_cvt_pk_bf16_f32 v162, v100, v101
	v_lshlrev_b32_e32 v244, 16, v163
	v_and_b32_e32 v245, 0xffff0000, v163
	v_fma_f32 v102, v102, 0.5, v244
	v_fma_f32 v103, v103, 0.5, v245
	v_fmac_f32_e32 v124, v102, v102
	v_fmac_f32_e32 v124, v103, v103
	v_cvt_pk_bf16_f32 v163, v102, v103
	v_lshlrev_b32_e32 v244, 16, v164
	v_and_b32_e32 v245, 0xffff0000, v164
	v_fma_f32 v96, v96, 0.5, v244
	v_fma_f32 v97, v97, 0.5, v245
	v_fmac_f32_e32 v124, v96, v96
	v_fmac_f32_e32 v124, v97, v97
	v_cvt_pk_bf16_f32 v164, v96, v97
	v_lshlrev_b32_e32 v244, 16, v165
	v_and_b32_e32 v245, 0xffff0000, v165
	v_fma_f32 v98, v98, 0.5, v244
	v_fma_f32 v99, v99, 0.5, v245
	v_fmac_f32_e32 v124, v98, v98
	v_fmac_f32_e32 v124, v99, v99
	v_cvt_pk_bf16_f32 v165, v98, v99
	global_store_dwordx4 v[236:237], v[162:165], off offset:256
	s_waitcnt vmcnt(14)
	s_mov_b32 s100, 0x20000
	v_lshl_add_u64 v[236:237], v[144:145], 0, s[100:101]
	v_lshlrev_b32_e32 v244, 16, v166
	v_and_b32_e32 v245, 0xffff0000, v166
	v_fma_f32 v92, v92, 0.5, v244
	v_fma_f32 v93, v93, 0.5, v245
	v_mul_f32_e32 v108, v92, v92
	v_fmac_f32_e32 v108, v93, v93
	v_cvt_pk_bf16_f32 v166, v92, v93
	v_lshlrev_b32_e32 v244, 16, v167
	v_and_b32_e32 v245, 0xffff0000, v167
	v_fma_f32 v94, v94, 0.5, v244
	v_fma_f32 v95, v95, 0.5, v245
	v_fmac_f32_e32 v108, v94, v94
	v_fmac_f32_e32 v108, v95, v95
	v_cvt_pk_bf16_f32 v167, v94, v95
	v_lshlrev_b32_e32 v244, 16, v168
	v_and_b32_e32 v245, 0xffff0000, v168
	v_fma_f32 v88, v88, 0.5, v244
	v_fma_f32 v89, v89, 0.5, v245
	v_fmac_f32_e32 v108, v88, v88
	v_fmac_f32_e32 v108, v89, v89
	v_cvt_pk_bf16_f32 v168, v88, v89
	v_lshlrev_b32_e32 v244, 16, v169
	v_and_b32_e32 v245, 0xffff0000, v169
	v_fma_f32 v90, v90, 0.5, v244
	v_fma_f32 v91, v91, 0.5, v245
	v_fmac_f32_e32 v108, v90, v90
	v_fmac_f32_e32 v108, v91, v91
	v_cvt_pk_bf16_f32 v169, v90, v91
	global_store_dwordx4 v[236:237], v[166:169], off
	v_lshlrev_b32_e32 v244, 16, v170
	v_and_b32_e32 v245, 0xffff0000, v170
	v_fma_f32 v84, v84, 0.5, v244
	v_fma_f32 v85, v85, 0.5, v245
	v_fmac_f32_e32 v108, v84, v84
	v_fmac_f32_e32 v108, v85, v85
	v_cvt_pk_bf16_f32 v170, v84, v85
	v_lshlrev_b32_e32 v244, 16, v171
	v_and_b32_e32 v245, 0xffff0000, v171
	v_fma_f32 v86, v86, 0.5, v244
	v_fma_f32 v87, v87, 0.5, v245
	v_fmac_f32_e32 v108, v86, v86
	v_fmac_f32_e32 v108, v87, v87
	v_cvt_pk_bf16_f32 v171, v86, v87
	v_lshlrev_b32_e32 v244, 16, v172
	v_and_b32_e32 v245, 0xffff0000, v172
	v_fma_f32 v80, v80, 0.5, v244
	v_fma_f32 v81, v81, 0.5, v245
	v_fmac_f32_e32 v108, v80, v80
	v_fmac_f32_e32 v108, v81, v81
	v_cvt_pk_bf16_f32 v172, v80, v81
	v_lshlrev_b32_e32 v244, 16, v173
	v_and_b32_e32 v245, 0xffff0000, v173
	v_fma_f32 v82, v82, 0.5, v244
	v_fma_f32 v83, v83, 0.5, v245
	v_fmac_f32_e32 v108, v82, v82
	v_fmac_f32_e32 v108, v83, v83
	v_cvt_pk_bf16_f32 v173, v82, v83
	global_store_dwordx4 v[236:237], v[170:173], off offset:256
	s_waitcnt vmcnt(14)
	s_mov_b32 s100, 0x30000
	v_lshl_add_u64 v[236:237], v[144:145], 0, s[100:101]
	v_lshlrev_b32_e32 v244, 16, v174
	v_and_b32_e32 v245, 0xffff0000, v174
	v_fma_f32 v76, v76, 0.5, v244
	v_fma_f32 v77, v77, 0.5, v245
	v_mul_f32_e32 v92, v76, v76
	v_fmac_f32_e32 v92, v77, v77
	v_cvt_pk_bf16_f32 v174, v76, v77
	v_lshlrev_b32_e32 v244, 16, v175
	v_and_b32_e32 v245, 0xffff0000, v175
	v_fma_f32 v78, v78, 0.5, v244
	v_fma_f32 v79, v79, 0.5, v245
	v_fmac_f32_e32 v92, v78, v78
	v_fmac_f32_e32 v92, v79, v79
	v_cvt_pk_bf16_f32 v175, v78, v79
	v_lshlrev_b32_e32 v244, 16, v176
	v_and_b32_e32 v245, 0xffff0000, v176
	v_fma_f32 v72, v72, 0.5, v244
	v_fma_f32 v73, v73, 0.5, v245
	v_fmac_f32_e32 v92, v72, v72
	v_fmac_f32_e32 v92, v73, v73
	v_cvt_pk_bf16_f32 v176, v72, v73
	v_lshlrev_b32_e32 v244, 16, v177
	v_and_b32_e32 v245, 0xffff0000, v177
	v_fma_f32 v74, v74, 0.5, v244
	v_fma_f32 v75, v75, 0.5, v245
	v_fmac_f32_e32 v92, v74, v74
	v_fmac_f32_e32 v92, v75, v75
	v_cvt_pk_bf16_f32 v177, v74, v75
	global_store_dwordx4 v[236:237], v[174:177], off
	v_lshlrev_b32_e32 v244, 16, v178
	v_and_b32_e32 v245, 0xffff0000, v178
	v_fma_f32 v68, v68, 0.5, v244
	v_fma_f32 v69, v69, 0.5, v245
	v_fmac_f32_e32 v92, v68, v68
	v_fmac_f32_e32 v92, v69, v69
	v_cvt_pk_bf16_f32 v178, v68, v69
	v_lshlrev_b32_e32 v244, 16, v179
	v_and_b32_e32 v245, 0xffff0000, v179
	v_fma_f32 v70, v70, 0.5, v244
	v_fma_f32 v71, v71, 0.5, v245
	v_fmac_f32_e32 v92, v70, v70
	v_fmac_f32_e32 v92, v71, v71
	v_cvt_pk_bf16_f32 v179, v70, v71
	v_lshlrev_b32_e32 v244, 16, v180
	v_and_b32_e32 v245, 0xffff0000, v180
	v_fma_f32 v64, v64, 0.5, v244
	v_fma_f32 v65, v65, 0.5, v245
	v_fmac_f32_e32 v92, v64, v64
	v_fmac_f32_e32 v92, v65, v65
	v_cvt_pk_bf16_f32 v180, v64, v65
	v_lshlrev_b32_e32 v244, 16, v181
	v_and_b32_e32 v245, 0xffff0000, v181
	v_fma_f32 v66, v66, 0.5, v244
	v_fma_f32 v67, v67, 0.5, v245
	v_fmac_f32_e32 v92, v66, v66
	v_fmac_f32_e32 v92, v67, v67
	v_cvt_pk_bf16_f32 v181, v66, v67
	global_store_dwordx4 v[236:237], v[178:181], off offset:256
	s_waitcnt vmcnt(14)
	s_mov_b32 s100, 0x80000
	v_lshl_add_u64 v[236:237], v[144:145], 0, s[100:101]
	v_lshlrev_b32_e32 v244, 16, v184
	v_and_b32_e32 v245, 0xffff0000, v184
	v_fma_f32 v60, v60, 0.5, v244
	v_fma_f32 v61, v61, 0.5, v245
	v_mul_f32_e32 v76, v60, v60
	v_fmac_f32_e32 v76, v61, v61
	v_cvt_pk_bf16_f32 v184, v60, v61
	v_lshlrev_b32_e32 v244, 16, v185
	v_and_b32_e32 v245, 0xffff0000, v185
	v_fma_f32 v62, v62, 0.5, v244
	v_fma_f32 v63, v63, 0.5, v245
	v_fmac_f32_e32 v76, v62, v62
	v_fmac_f32_e32 v76, v63, v63
	v_cvt_pk_bf16_f32 v185, v62, v63
	v_lshlrev_b32_e32 v244, 16, v186
	v_and_b32_e32 v245, 0xffff0000, v186
	v_fma_f32 v56, v56, 0.5, v244
	v_fma_f32 v57, v57, 0.5, v245
	v_fmac_f32_e32 v76, v56, v56
	v_fmac_f32_e32 v76, v57, v57
	v_cvt_pk_bf16_f32 v186, v56, v57
	v_lshlrev_b32_e32 v244, 16, v187
	v_and_b32_e32 v245, 0xffff0000, v187
	v_fma_f32 v58, v58, 0.5, v244
	v_fma_f32 v59, v59, 0.5, v245
	v_fmac_f32_e32 v76, v58, v58
	v_fmac_f32_e32 v76, v59, v59
	v_cvt_pk_bf16_f32 v187, v58, v59
	global_store_dwordx4 v[236:237], v[184:187], off
	v_lshlrev_b32_e32 v244, 16, v190
	v_and_b32_e32 v245, 0xffff0000, v190
	v_fma_f32 v52, v52, 0.5, v244
	v_fma_f32 v53, v53, 0.5, v245
	v_fmac_f32_e32 v76, v52, v52
	v_fmac_f32_e32 v76, v53, v53
	v_cvt_pk_bf16_f32 v190, v52, v53
	v_lshlrev_b32_e32 v244, 16, v191
	v_and_b32_e32 v245, 0xffff0000, v191
	v_fma_f32 v54, v54, 0.5, v244
	v_fma_f32 v55, v55, 0.5, v245
	v_fmac_f32_e32 v76, v54, v54
	v_fmac_f32_e32 v76, v55, v55
	v_cvt_pk_bf16_f32 v191, v54, v55
	v_lshlrev_b32_e32 v244, 16, v192
	v_and_b32_e32 v245, 0xffff0000, v192
	v_fma_f32 v48, v48, 0.5, v244
	v_fma_f32 v49, v49, 0.5, v245
	v_fmac_f32_e32 v76, v48, v48
	v_fmac_f32_e32 v76, v49, v49
	v_cvt_pk_bf16_f32 v192, v48, v49
	v_lshlrev_b32_e32 v244, 16, v193
	v_and_b32_e32 v245, 0xffff0000, v193
	v_fma_f32 v50, v50, 0.5, v244
	v_fma_f32 v51, v51, 0.5, v245
	v_fmac_f32_e32 v76, v50, v50
	v_fmac_f32_e32 v76, v51, v51
	v_cvt_pk_bf16_f32 v193, v50, v51
	global_store_dwordx4 v[236:237], v[190:193], off offset:256
	s_waitcnt vmcnt(14)
	s_mov_b32 s100, 0x90000
	v_lshl_add_u64 v[236:237], v[144:145], 0, s[100:101]
	v_lshlrev_b32_e32 v244, 16, v194
	v_and_b32_e32 v245, 0xffff0000, v194
	v_fma_f32 v44, v44, 0.5, v244
	v_fma_f32 v45, v45, 0.5, v245
	v_mul_f32_e32 v60, v44, v44
	v_fmac_f32_e32 v60, v45, v45
	v_cvt_pk_bf16_f32 v194, v44, v45
	v_lshlrev_b32_e32 v244, 16, v195
	v_and_b32_e32 v245, 0xffff0000, v195
	v_fma_f32 v46, v46, 0.5, v244
	v_fma_f32 v47, v47, 0.5, v245
	v_fmac_f32_e32 v60, v46, v46
	v_fmac_f32_e32 v60, v47, v47
	v_cvt_pk_bf16_f32 v195, v46, v47
	v_lshlrev_b32_e32 v244, 16, v196
	v_and_b32_e32 v245, 0xffff0000, v196
	v_fma_f32 v40, v40, 0.5, v244
	v_fma_f32 v41, v41, 0.5, v245
	v_fmac_f32_e32 v60, v40, v40
	v_fmac_f32_e32 v60, v41, v41
	v_cvt_pk_bf16_f32 v196, v40, v41
	v_lshlrev_b32_e32 v244, 16, v197
	v_and_b32_e32 v245, 0xffff0000, v197
	v_fma_f32 v42, v42, 0.5, v244
	v_fma_f32 v43, v43, 0.5, v245
	v_fmac_f32_e32 v60, v42, v42
	v_fmac_f32_e32 v60, v43, v43
	v_cvt_pk_bf16_f32 v197, v42, v43
	global_store_dwordx4 v[236:237], v[194:197], off
	v_lshlrev_b32_e32 v244, 16, v198
	v_and_b32_e32 v245, 0xffff0000, v198
	v_fma_f32 v36, v36, 0.5, v244
	v_fma_f32 v37, v37, 0.5, v245
	v_fmac_f32_e32 v60, v36, v36
	v_fmac_f32_e32 v60, v37, v37
	v_cvt_pk_bf16_f32 v198, v36, v37
	v_lshlrev_b32_e32 v244, 16, v199
	v_and_b32_e32 v245, 0xffff0000, v199
	v_fma_f32 v38, v38, 0.5, v244
	v_fma_f32 v39, v39, 0.5, v245
	v_fmac_f32_e32 v60, v38, v38
	v_fmac_f32_e32 v60, v39, v39
	v_cvt_pk_bf16_f32 v199, v38, v39
	v_lshlrev_b32_e32 v244, 16, v200
	v_and_b32_e32 v245, 0xffff0000, v200
	v_fma_f32 v32, v32, 0.5, v244
	v_fma_f32 v33, v33, 0.5, v245
	v_fmac_f32_e32 v60, v32, v32
	v_fmac_f32_e32 v60, v33, v33
	v_cvt_pk_bf16_f32 v200, v32, v33
	v_lshlrev_b32_e32 v244, 16, v201
	v_and_b32_e32 v245, 0xffff0000, v201
	v_fma_f32 v34, v34, 0.5, v244
	v_fma_f32 v35, v35, 0.5, v245
	v_fmac_f32_e32 v60, v34, v34
	v_fmac_f32_e32 v60, v35, v35
	v_cvt_pk_bf16_f32 v201, v34, v35
	global_store_dwordx4 v[236:237], v[198:201], off offset:256
	s_waitcnt vmcnt(14)
	s_mov_b32 s100, 0xa0000
	v_lshl_add_u64 v[236:237], v[144:145], 0, s[100:101]
	v_lshlrev_b32_e32 v244, 16, v202
	v_and_b32_e32 v245, 0xffff0000, v202
	v_fma_f32 v28, v28, 0.5, v244
	v_fma_f32 v29, v29, 0.5, v245
	v_mul_f32_e32 v44, v28, v28
	v_fmac_f32_e32 v44, v29, v29
	v_cvt_pk_bf16_f32 v202, v28, v29
	v_lshlrev_b32_e32 v244, 16, v203
	v_and_b32_e32 v245, 0xffff0000, v203
	v_fma_f32 v30, v30, 0.5, v244
	v_fma_f32 v31, v31, 0.5, v245
	v_fmac_f32_e32 v44, v30, v30
	v_fmac_f32_e32 v44, v31, v31
	v_cvt_pk_bf16_f32 v203, v30, v31
	v_lshlrev_b32_e32 v244, 16, v204
	v_and_b32_e32 v245, 0xffff0000, v204
	v_fma_f32 v24, v24, 0.5, v244
	v_fma_f32 v25, v25, 0.5, v245
	v_fmac_f32_e32 v44, v24, v24
	v_fmac_f32_e32 v44, v25, v25
	v_cvt_pk_bf16_f32 v204, v24, v25
	v_lshlrev_b32_e32 v244, 16, v205
	v_and_b32_e32 v245, 0xffff0000, v205
	v_fma_f32 v26, v26, 0.5, v244
	v_fma_f32 v27, v27, 0.5, v245
	v_fmac_f32_e32 v44, v26, v26
	v_fmac_f32_e32 v44, v27, v27
	v_cvt_pk_bf16_f32 v205, v26, v27
	global_store_dwordx4 v[236:237], v[202:205], off
	v_lshlrev_b32_e32 v244, 16, v206
	v_and_b32_e32 v245, 0xffff0000, v206
	v_fma_f32 v20, v20, 0.5, v244
	v_fma_f32 v21, v21, 0.5, v245
	v_fmac_f32_e32 v44, v20, v20
	v_fmac_f32_e32 v44, v21, v21
	v_cvt_pk_bf16_f32 v206, v20, v21
	v_lshlrev_b32_e32 v244, 16, v207
	v_and_b32_e32 v245, 0xffff0000, v207
	v_fma_f32 v22, v22, 0.5, v244
	v_fma_f32 v23, v23, 0.5, v245
	v_fmac_f32_e32 v44, v22, v22
	v_fmac_f32_e32 v44, v23, v23
	v_cvt_pk_bf16_f32 v207, v22, v23
	v_lshlrev_b32_e32 v244, 16, v208
	v_and_b32_e32 v245, 0xffff0000, v208
	v_fma_f32 v16, v16, 0.5, v244
	v_fma_f32 v17, v17, 0.5, v245
	v_fmac_f32_e32 v44, v16, v16
	v_fmac_f32_e32 v44, v17, v17
	v_cvt_pk_bf16_f32 v208, v16, v17
	v_lshlrev_b32_e32 v244, 16, v209
	v_and_b32_e32 v245, 0xffff0000, v209
	v_fma_f32 v18, v18, 0.5, v244
	v_fma_f32 v19, v19, 0.5, v245
	v_fmac_f32_e32 v44, v18, v18
	v_fmac_f32_e32 v44, v19, v19
	v_cvt_pk_bf16_f32 v209, v18, v19
	global_store_dwordx4 v[236:237], v[206:209], off offset:256
	s_waitcnt vmcnt(14)
	s_mov_b32 s100, 0xb0000
	v_lshl_add_u64 v[236:237], v[144:145], 0, s[100:101]
	v_lshlrev_b32_e32 v244, 16, v210
	v_and_b32_e32 v245, 0xffff0000, v210
	v_fma_f32 v12, v12, 0.5, v244
	v_fma_f32 v13, v13, 0.5, v245
	v_mul_f32_e32 v28, v12, v12
	v_fmac_f32_e32 v28, v13, v13
	v_cvt_pk_bf16_f32 v210, v12, v13
	v_lshlrev_b32_e32 v244, 16, v211
	v_and_b32_e32 v245, 0xffff0000, v211
	v_fma_f32 v14, v14, 0.5, v244
	v_fma_f32 v15, v15, 0.5, v245
	v_fmac_f32_e32 v28, v14, v14
	v_fmac_f32_e32 v28, v15, v15
	v_cvt_pk_bf16_f32 v211, v14, v15
	v_lshlrev_b32_e32 v244, 16, v212
	v_and_b32_e32 v245, 0xffff0000, v212
	v_fma_f32 v8, v8, 0.5, v244
	v_fma_f32 v9, v9, 0.5, v245
	v_fmac_f32_e32 v28, v8, v8
	v_fmac_f32_e32 v28, v9, v9
	v_cvt_pk_bf16_f32 v212, v8, v9
	v_lshlrev_b32_e32 v244, 16, v213
	v_and_b32_e32 v245, 0xffff0000, v213
	v_fma_f32 v10, v10, 0.5, v244
	v_fma_f32 v11, v11, 0.5, v245
	v_fmac_f32_e32 v28, v10, v10
	v_fmac_f32_e32 v28, v11, v11
	v_cvt_pk_bf16_f32 v213, v10, v11
	global_store_dwordx4 v[236:237], v[210:213], off
	v_lshlrev_b32_e32 v244, 16, v214
	v_and_b32_e32 v245, 0xffff0000, v214
	v_fma_f32 v4, v4, 0.5, v244
	v_fma_f32 v5, v5, 0.5, v245
	v_fmac_f32_e32 v28, v4, v4
	v_fmac_f32_e32 v28, v5, v5
	v_cvt_pk_bf16_f32 v214, v4, v5
	v_lshlrev_b32_e32 v244, 16, v215
	v_and_b32_e32 v245, 0xffff0000, v215
	v_fma_f32 v6, v6, 0.5, v244
	v_fma_f32 v7, v7, 0.5, v245
	v_fmac_f32_e32 v28, v6, v6
	v_fmac_f32_e32 v28, v7, v7
	v_cvt_pk_bf16_f32 v215, v6, v7
	v_lshlrev_b32_e32 v244, 16, v216
	v_and_b32_e32 v245, 0xffff0000, v216
	v_fma_f32 v0, v0, 0.5, v244
	v_fma_f32 v1, v1, 0.5, v245
	v_fmac_f32_e32 v28, v0, v0
	v_fmac_f32_e32 v28, v1, v1
	v_cvt_pk_bf16_f32 v216, v0, v1
	v_lshlrev_b32_e32 v244, 16, v217
	v_and_b32_e32 v245, 0xffff0000, v217
	v_fma_f32 v2, v2, 0.5, v244
	v_fma_f32 v3, v3, 0.5, v245
	v_fmac_f32_e32 v28, v2, v2
	v_fmac_f32_e32 v28, v3, v3
	v_cvt_pk_bf16_f32 v217, v2, v3
	global_store_dwordx4 v[236:237], v[214:217], off offset:256
	ds_bpermute_b32 v0, v153, v243
	ds_bpermute_b32 v1, v153, v124
	ds_bpermute_b32 v2, v153, v108
	ds_bpermute_b32 v3, v153, v92
	ds_bpermute_b32 v8, v153, v76
	ds_bpermute_b32 v9, v153, v60
	ds_bpermute_b32 v10, v153, v44
	ds_bpermute_b32 v11, v153, v28
	s_waitcnt lgkmcnt(7)
	v_add_f32_e32 v243, v243, v0
	s_waitcnt lgkmcnt(6)
	v_add_f32_e32 v124, v124, v1
	s_waitcnt lgkmcnt(5)
	v_add_f32_e32 v108, v108, v2
	s_waitcnt lgkmcnt(4)
	v_add_f32_e32 v92, v92, v3
	s_waitcnt lgkmcnt(3)
	v_add_f32_e32 v76, v76, v8
	s_waitcnt lgkmcnt(2)
	v_add_f32_e32 v60, v60, v9
	s_waitcnt lgkmcnt(1)
	v_add_f32_e32 v44, v44, v10
	s_waitcnt lgkmcnt(0)
	v_add_f32_e32 v28, v28, v11
	ds_bpermute_b32 v0, v242, v243
	ds_bpermute_b32 v1, v242, v124
	ds_bpermute_b32 v2, v242, v108
	ds_bpermute_b32 v3, v242, v92
	ds_bpermute_b32 v8, v242, v76
	ds_bpermute_b32 v9, v242, v60
	ds_bpermute_b32 v10, v242, v44
	ds_bpermute_b32 v11, v242, v28
	s_waitcnt lgkmcnt(7)
	v_add_f32_e32 v243, v243, v0
	s_waitcnt lgkmcnt(6)
	v_add_f32_e32 v124, v124, v1
	s_waitcnt lgkmcnt(5)
	v_add_f32_e32 v108, v108, v2
	s_waitcnt lgkmcnt(4)
	v_add_f32_e32 v92, v92, v3
	s_waitcnt lgkmcnt(3)
	v_add_f32_e32 v76, v76, v8
	s_waitcnt lgkmcnt(2)
	v_add_f32_e32 v60, v60, v9
	s_waitcnt lgkmcnt(1)
	v_add_f32_e32 v44, v44, v10
	s_waitcnt lgkmcnt(0)
	v_add_f32_e32 v28, v28, v11
	s_and_saveexec_b64 s[20:21], s[4:5]
	v_lshl_add_u64 v[144:145], v[238:239], 3, s[16:17]
	v_mul_f32_e32 v243, 0x4f800000, v243
	v_trunc_f32_e32 v243, v243
	v_mul_f32_e32 v0, 0x2f800000, v243
	v_floor_f32_e32 v0, v0
	v_fmac_f32_e32 v243, 0xcf800000, v0
	v_cvt_u32_f32_e32 v244, v243
	v_cvt_u32_f32_e32 v245, v0
	global_atomic_add_x2 v[144:145], v[244:245], off
	s_nop 1
	v_mul_f32_e32 v124, 0x4f800000, v124
	v_trunc_f32_e32 v124, v124
	v_mul_f32_e32 v1, 0x2f800000, v124
	v_floor_f32_e32 v1, v1
	v_fmac_f32_e32 v124, 0xcf800000, v1
	v_cvt_u32_f32_e32 v244, v124
	v_cvt_u32_f32_e32 v245, v1
	global_atomic_add_x2 v[144:145], v[244:245], off offset:128
	s_nop 1
	v_mul_f32_e32 v108, 0x4f800000, v108
	v_trunc_f32_e32 v108, v108
	v_mul_f32_e32 v2, 0x2f800000, v108
	v_floor_f32_e32 v2, v2
	v_fmac_f32_e32 v108, 0xcf800000, v2
	v_cvt_u32_f32_e32 v244, v108
	v_cvt_u32_f32_e32 v245, v2
	global_atomic_add_x2 v[144:145], v[244:245], off offset:256
	s_nop 1
	v_mul_f32_e32 v92, 0x4f800000, v92
	v_trunc_f32_e32 v92, v92
	v_mul_f32_e32 v3, 0x2f800000, v92
	v_floor_f32_e32 v3, v3
	v_fmac_f32_e32 v92, 0xcf800000, v3
	v_cvt_u32_f32_e32 v244, v92
	v_cvt_u32_f32_e32 v245, v3
	global_atomic_add_x2 v[144:145], v[244:245], off offset:384
	s_nop 1
	v_mul_f32_e32 v76, 0x4f800000, v76
	v_trunc_f32_e32 v76, v76
	v_mul_f32_e32 v8, 0x2f800000, v76
	v_floor_f32_e32 v8, v8
	v_fmac_f32_e32 v76, 0xcf800000, v8
	v_cvt_u32_f32_e32 v244, v76
	v_cvt_u32_f32_e32 v245, v8
	global_atomic_add_x2 v[144:145], v[244:245], off offset:1024
	s_nop 1
	v_mul_f32_e32 v60, 0x4f800000, v60
	v_trunc_f32_e32 v60, v60
	v_mul_f32_e32 v9, 0x2f800000, v60
	v_floor_f32_e32 v9, v9
	v_fmac_f32_e32 v60, 0xcf800000, v9
	v_cvt_u32_f32_e32 v244, v60
	v_cvt_u32_f32_e32 v245, v9
	global_atomic_add_x2 v[144:145], v[244:245], off offset:1152
	s_nop 1
	v_mul_f32_e32 v44, 0x4f800000, v44
	v_trunc_f32_e32 v44, v44
	v_mul_f32_e32 v10, 0x2f800000, v44
	v_floor_f32_e32 v10, v10
	v_fmac_f32_e32 v44, 0xcf800000, v10
	v_cvt_u32_f32_e32 v244, v44
	v_cvt_u32_f32_e32 v245, v10
	global_atomic_add_x2 v[144:145], v[244:245], off offset:1280
	s_nop 1
	v_mul_f32_e32 v28, 0x4f800000, v28
	v_trunc_f32_e32 v28, v28
	v_mul_f32_e32 v11, 0x2f800000, v28
	v_floor_f32_e32 v11, v11
	v_fmac_f32_e32 v28, 0xcf800000, v11
	v_cvt_u32_f32_e32 v244, v28
	v_cvt_u32_f32_e32 v245, v11
	global_atomic_add_x2 v[144:145], v[244:245], off offset:1408
	s_nop 1

.LBB0_2215:
	s_mov_b32 s52, s56
	v_lshl_add_u32 v240, s24, 8, v144
	v_and_b32_e32 v242, 0xe0, v146
	v_and_b32_e32 v243, 4, v146
	v_lshl_or_b32 v242, v243, 2, v242
	v_and_b32_e32 v243, 8, v146
	v_or_b32_e32 v242, v242, v243
	v_lshl_or_b32 v242, s26, 8, v242
	v_mov_b32_e32 v243, 0
	v_ashrrev_i32_e32 v241, 31, v240
	v_readlane_b32 s24, v234, 22
	v_readlane_b32 s25, v234, 23
	v_lshlrev_b64 v[246:247], 11, v[240:241]
	v_lshl_add_u64 v[246:247], v[246:247], 0, v[242:243]
	v_lshl_add_u64 v[236:237], v[246:247], 1, s[24:25]
	s_mov_b32 s101, 0
	global_load_dwordx4 v[140:143], v[236:237], off
	global_load_dwordx4 v[154:157], v[236:237], off offset:256
	s_mov_b32 s100, 0x10000
	v_lshl_add_u64 v[238:239], v[236:237], 0, s[100:101]
	global_load_dwordx4 v[158:161], v[238:239], off
	global_load_dwordx4 v[162:165], v[238:239], off offset:256
	s_mov_b32 s100, 0x20000
	v_lshl_add_u64 v[238:239], v[236:237], 0, s[100:101]
	global_load_dwordx4 v[166:169], v[238:239], off
	global_load_dwordx4 v[170:173], v[238:239], off offset:256
	s_mov_b32 s100, 0x30000
	v_lshl_add_u64 v[238:239], v[236:237], 0, s[100:101]
	global_load_dwordx4 v[174:177], v[238:239], off
	global_load_dwordx4 v[178:181], v[238:239], off offset:256
	s_mov_b32 s100, 0x80000
	v_lshl_add_u64 v[238:239], v[236:237], 0, s[100:101]
	global_load_dwordx4 v[184:187], v[238:239], off
	global_load_dwordx4 v[188:191], v[238:239], off offset:256
	s_mov_b32 s100, 0x90000
	v_lshl_add_u64 v[238:239], v[236:237], 0, s[100:101]
	global_load_dwordx4 v[192:195], v[238:239], off
	global_load_dwordx4 v[196:199], v[238:239], off offset:256
	s_mov_b32 s100, 0xa0000
	v_lshl_add_u64 v[238:239], v[236:237], 0, s[100:101]
	global_load_dwordx4 v[200:203], v[238:239], off
	global_load_dwordx4 v[204:207], v[238:239], off offset:256
	s_mov_b32 s100, 0xb0000
	v_lshl_add_u64 v[238:239], v[236:237], 0, s[100:101]
	global_load_dwordx4 v[208:211], v[238:239], off
	global_load_dwordx4 v[212:215], v[238:239], off offset:256
	v_lshlrev_b32_e32 v244, 2, v150
	v_lshlrev_b32_e32 v245, 2, v151
	v_permlane16_swap_b32_e32 v124, v120
	v_permlane16_swap_b32_e32 v125, v121
	v_permlane16_swap_b32_e32 v126, v122
	v_permlane16_swap_b32_e32 v127, v123
	v_permlane16_swap_b32_e32 v116, v112
	v_permlane16_swap_b32_e32 v117, v113
	v_permlane16_swap_b32_e32 v118, v114
	v_permlane16_swap_b32_e32 v119, v115
	v_permlane16_swap_b32_e32 v108, v104
	v_permlane16_swap_b32_e32 v109, v105
	v_permlane16_swap_b32_e32 v110, v106
	v_permlane16_swap_b32_e32 v111, v107
	v_permlane16_swap_b32_e32 v100, v96
	v_permlane16_swap_b32_e32 v101, v97
	v_permlane16_swap_b32_e32 v102, v98
	v_permlane16_swap_b32_e32 v103, v99
	v_permlane16_swap_b32_e32 v92, v88
	v_permlane16_swap_b32_e32 v93, v89
	v_permlane16_swap_b32_e32 v94, v90
	v_permlane16_swap_b32_e32 v95, v91
	v_permlane16_swap_b32_e32 v84, v80
	v_permlane16_swap_b32_e32 v85, v81
	v_permlane16_swap_b32_e32 v86, v82
	v_permlane16_swap_b32_e32 v87, v83
	v_permlane16_swap_b32_e32 v76, v72
	v_permlane16_swap_b32_e32 v77, v73
	v_permlane16_swap_b32_e32 v78, v74
	v_permlane16_swap_b32_e32 v79, v75
	v_permlane16_swap_b32_e32 v68, v64
	v_permlane16_swap_b32_e32 v69, v65
	v_permlane16_swap_b32_e32 v70, v66
	v_permlane16_swap_b32_e32 v71, v67
	v_permlane16_swap_b32_e32 v60, v56
	v_permlane16_swap_b32_e32 v61, v57
	v_permlane16_swap_b32_e32 v62, v58
	v_permlane16_swap_b32_e32 v63, v59
	v_permlane16_swap_b32_e32 v52, v48
	v_permlane16_swap_b32_e32 v53, v49
	v_permlane16_swap_b32_e32 v54, v50
	v_permlane16_swap_b32_e32 v55, v51
	v_permlane16_swap_b32_e32 v44, v40
	v_permlane16_swap_b32_e32 v45, v41
	v_permlane16_swap_b32_e32 v46, v42
	v_permlane16_swap_b32_e32 v47, v43
	v_permlane16_swap_b32_e32 v36, v32
	v_permlane16_swap_b32_e32 v37, v33
	v_permlane16_swap_b32_e32 v38, v34
	v_permlane16_swap_b32_e32 v39, v35
	v_permlane16_swap_b32_e32 v28, v24
	v_permlane16_swap_b32_e32 v29, v25
	v_permlane16_swap_b32_e32 v30, v26
	v_permlane16_swap_b32_e32 v31, v27
	v_permlane16_swap_b32_e32 v20, v16
	v_permlane16_swap_b32_e32 v21, v17
	v_permlane16_swap_b32_e32 v22, v18
	v_permlane16_swap_b32_e32 v23, v19
	v_permlane16_swap_b32_e32 v12, v8
	v_permlane16_swap_b32_e32 v13, v9
	v_permlane16_swap_b32_e32 v14, v10
	v_permlane16_swap_b32_e32 v15, v11
	v_permlane16_swap_b32_e32 v4, v0
	v_permlane16_swap_b32_e32 v5, v1
	v_permlane16_swap_b32_e32 v6, v2
	v_permlane16_swap_b32_e32 v7, v3
	s_waitcnt vmcnt(14)
	v_lshlrev_b32_e32 v246, 16, v140
	v_and_b32_e32 v247, 0xffff0000, v140
	v_add_f32_e32 v124, v124, v246
	v_add_f32_e32 v125, v125, v247
	v_mul_f32_e32 v248, v124, v124
	v_fmac_f32_e32 v248, v125, v125
	v_cvt_pk_bf16_f32 v140, v124, v125
	v_lshlrev_b32_e32 v246, 16, v141
	v_and_b32_e32 v247, 0xffff0000, v141
	v_add_f32_e32 v126, v126, v246
	v_add_f32_e32 v127, v127, v247
	v_fmac_f32_e32 v248, v126, v126
	v_fmac_f32_e32 v248, v127, v127
	v_cvt_pk_bf16_f32 v141, v126, v127
	v_lshlrev_b32_e32 v246, 16, v142
	v_and_b32_e32 v247, 0xffff0000, v142
	v_add_f32_e32 v120, v120, v246
	v_add_f32_e32 v121, v121, v247
	v_fmac_f32_e32 v248, v120, v120
	v_fmac_f32_e32 v248, v121, v121
	v_cvt_pk_bf16_f32 v142, v120, v121
	v_lshlrev_b32_e32 v246, 16, v143
	v_and_b32_e32 v247, 0xffff0000, v143
	v_add_f32_e32 v122, v122, v246
	v_add_f32_e32 v123, v123, v247
	v_fmac_f32_e32 v248, v122, v122
	v_fmac_f32_e32 v248, v123, v123
	v_cvt_pk_bf16_f32 v143, v122, v123
	global_store_dwordx4 v[236:237], v[140:143], off
	v_lshlrev_b32_e32 v246, 16, v154
	v_and_b32_e32 v247, 0xffff0000, v154
	v_add_f32_e32 v116, v116, v246
	v_add_f32_e32 v117, v117, v247
	v_fmac_f32_e32 v248, v116, v116
	v_fmac_f32_e32 v248, v117, v117
	v_cvt_pk_bf16_f32 v154, v116, v117
	v_lshlrev_b32_e32 v246, 16, v155
	v_and_b32_e32 v247, 0xffff0000, v155
	v_add_f32_e32 v118, v118, v246
	v_add_f32_e32 v119, v119, v247
	v_fmac_f32_e32 v248, v118, v118
	v_fmac_f32_e32 v248, v119, v119
	v_cvt_pk_bf16_f32 v155, v118, v119
	v_lshlrev_b32_e32 v246, 16, v156
	v_and_b32_e32 v247, 0xffff0000, v156
	v_add_f32_e32 v112, v112, v246
	v_add_f32_e32 v113, v113, v247
	v_fmac_f32_e32 v248, v112, v112
	v_fmac_f32_e32 v248, v113, v113
	v_cvt_pk_bf16_f32 v156, v112, v113
	v_lshlrev_b32_e32 v246, 16, v157
	v_and_b32_e32 v247, 0xffff0000, v157
	v_add_f32_e32 v114, v114, v246
	v_add_f32_e32 v115, v115, v247
	v_fmac_f32_e32 v248, v114, v114
	v_fmac_f32_e32 v248, v115, v115
	v_cvt_pk_bf16_f32 v157, v114, v115
	global_store_dwordx4 v[236:237], v[154:157], off offset:256
	s_waitcnt vmcnt(14)
	s_mov_b32 s100, 0x10000
	v_lshl_add_u64 v[238:239], v[236:237], 0, s[100:101]
	v_lshlrev_b32_e32 v246, 16, v158
	v_and_b32_e32 v247, 0xffff0000, v158
	v_add_f32_e32 v108, v108, v246
	v_add_f32_e32 v109, v109, v247
	v_mul_f32_e32 v124, v108, v108
	v_fmac_f32_e32 v124, v109, v109
	v_cvt_pk_bf16_f32 v158, v108, v109
	v_lshlrev_b32_e32 v246, 16, v159
	v_and_b32_e32 v247, 0xffff0000, v159
	v_add_f32_e32 v110, v110, v246
	v_add_f32_e32 v111, v111, v247
	v_fmac_f32_e32 v124, v110, v110
	v_fmac_f32_e32 v124, v111, v111
	v_cvt_pk_bf16_f32 v159, v110, v111
	v_lshlrev_b32_e32 v246, 16, v160
	v_and_b32_e32 v247, 0xffff0000, v160
	v_add_f32_e32 v104, v104, v246
	v_add_f32_e32 v105, v105, v247
	v_fmac_f32_e32 v124, v104, v104
	v_fmac_f32_e32 v124, v105, v105
	v_cvt_pk_bf16_f32 v160, v104, v105
	v_lshlrev_b32_e32 v246, 16, v161
	v_and_b32_e32 v247, 0xffff0000, v161
	v_add_f32_e32 v106, v106, v246
	v_add_f32_e32 v107, v107, v247
	v_fmac_f32_e32 v124, v106, v106
	v_fmac_f32_e32 v124, v107, v107
	v_cvt_pk_bf16_f32 v161, v106, v107
	global_store_dwordx4 v[238:239], v[158:161], off
	v_lshlrev_b32_e32 v246, 16, v162
	v_and_b32_e32 v247, 0xffff0000, v162
	v_add_f32_e32 v100, v100, v246
	v_add_f32_e32 v101, v101, v247
	v_fmac_f32_e32 v124, v100, v100
	v_fmac_f32_e32 v124, v101, v101
	v_cvt_pk_bf16_f32 v162, v100, v101
	v_lshlrev_b32_e32 v246, 16, v163
	v_and_b32_e32 v247, 0xffff0000, v163
	v_add_f32_e32 v102, v102, v246
	v_add_f32_e32 v103, v103, v247
	v_fmac_f32_e32 v124, v102, v102
	v_fmac_f32_e32 v124, v103, v103
	v_cvt_pk_bf16_f32 v163, v102, v103
	v_lshlrev_b32_e32 v246, 16, v164
	v_and_b32_e32 v247, 0xffff0000, v164
	v_add_f32_e32 v96, v96, v246
	v_add_f32_e32 v97, v97, v247
	v_fmac_f32_e32 v124, v96, v96
	v_fmac_f32_e32 v124, v97, v97
	v_cvt_pk_bf16_f32 v164, v96, v97
	v_lshlrev_b32_e32 v246, 16, v165
	v_and_b32_e32 v247, 0xffff0000, v165
	v_add_f32_e32 v98, v98, v246
	v_add_f32_e32 v99, v99, v247
	v_fmac_f32_e32 v124, v98, v98
	v_fmac_f32_e32 v124, v99, v99
	v_cvt_pk_bf16_f32 v165, v98, v99
	global_store_dwordx4 v[238:239], v[162:165], off offset:256
	s_waitcnt vmcnt(14)
	s_mov_b32 s100, 0x20000
	v_lshl_add_u64 v[238:239], v[236:237], 0, s[100:101]
	v_lshlrev_b32_e32 v246, 16, v166
	v_and_b32_e32 v247, 0xffff0000, v166
	v_add_f32_e32 v92, v92, v246
	v_add_f32_e32 v93, v93, v247
	v_mul_f32_e32 v108, v92, v92
	v_fmac_f32_e32 v108, v93, v93
	v_cvt_pk_bf16_f32 v166, v92, v93
	v_lshlrev_b32_e32 v246, 16, v167
	v_and_b32_e32 v247, 0xffff0000, v167
	v_add_f32_e32 v94, v94, v246
	v_add_f32_e32 v95, v95, v247
	v_fmac_f32_e32 v108, v94, v94
	v_fmac_f32_e32 v108, v95, v95
	v_cvt_pk_bf16_f32 v167, v94, v95
	v_lshlrev_b32_e32 v246, 16, v168
	v_and_b32_e32 v247, 0xffff0000, v168
	v_add_f32_e32 v88, v88, v246
	v_add_f32_e32 v89, v89, v247
	v_fmac_f32_e32 v108, v88, v88
	v_fmac_f32_e32 v108, v89, v89
	v_cvt_pk_bf16_f32 v168, v88, v89
	v_lshlrev_b32_e32 v246, 16, v169
	v_and_b32_e32 v247, 0xffff0000, v169
	v_add_f32_e32 v90, v90, v246
	v_add_f32_e32 v91, v91, v247
	v_fmac_f32_e32 v108, v90, v90
	v_fmac_f32_e32 v108, v91, v91
	v_cvt_pk_bf16_f32 v169, v90, v91
	global_store_dwordx4 v[238:239], v[166:169], off
	v_lshlrev_b32_e32 v246, 16, v170
	v_and_b32_e32 v247, 0xffff0000, v170
	v_add_f32_e32 v84, v84, v246
	v_add_f32_e32 v85, v85, v247
	v_fmac_f32_e32 v108, v84, v84
	v_fmac_f32_e32 v108, v85, v85
	v_cvt_pk_bf16_f32 v170, v84, v85
	v_lshlrev_b32_e32 v246, 16, v171
	v_and_b32_e32 v247, 0xffff0000, v171
	v_add_f32_e32 v86, v86, v246
	v_add_f32_e32 v87, v87, v247
	v_fmac_f32_e32 v108, v86, v86
	v_fmac_f32_e32 v108, v87, v87
	v_cvt_pk_bf16_f32 v171, v86, v87
	v_lshlrev_b32_e32 v246, 16, v172
	v_and_b32_e32 v247, 0xffff0000, v172
	v_add_f32_e32 v80, v80, v246
	v_add_f32_e32 v81, v81, v247
	v_fmac_f32_e32 v108, v80, v80
	v_fmac_f32_e32 v108, v81, v81
	v_cvt_pk_bf16_f32 v172, v80, v81
	v_lshlrev_b32_e32 v246, 16, v173
	v_and_b32_e32 v247, 0xffff0000, v173
	v_add_f32_e32 v82, v82, v246
	v_add_f32_e32 v83, v83, v247
	v_fmac_f32_e32 v108, v82, v82
	v_fmac_f32_e32 v108, v83, v83
	v_cvt_pk_bf16_f32 v173, v82, v83
	global_store_dwordx4 v[238:239], v[170:173], off offset:256
	s_waitcnt vmcnt(14)
	s_mov_b32 s100, 0x30000
	v_lshl_add_u64 v[238:239], v[236:237], 0, s[100:101]
	v_lshlrev_b32_e32 v246, 16, v174
	v_and_b32_e32 v247, 0xffff0000, v174
	v_add_f32_e32 v76, v76, v246
	v_add_f32_e32 v77, v77, v247
	v_mul_f32_e32 v92, v76, v76
	v_fmac_f32_e32 v92, v77, v77
	v_cvt_pk_bf16_f32 v174, v76, v77
	v_lshlrev_b32_e32 v246, 16, v175
	v_and_b32_e32 v247, 0xffff0000, v175
	v_add_f32_e32 v78, v78, v246
	v_add_f32_e32 v79, v79, v247
	v_fmac_f32_e32 v92, v78, v78
	v_fmac_f32_e32 v92, v79, v79
	v_cvt_pk_bf16_f32 v175, v78, v79
	v_lshlrev_b32_e32 v246, 16, v176
	v_and_b32_e32 v247, 0xffff0000, v176
	v_add_f32_e32 v72, v72, v246
	v_add_f32_e32 v73, v73, v247
	v_fmac_f32_e32 v92, v72, v72
	v_fmac_f32_e32 v92, v73, v73
	v_cvt_pk_bf16_f32 v176, v72, v73
	v_lshlrev_b32_e32 v246, 16, v177
	v_and_b32_e32 v247, 0xffff0000, v177
	v_add_f32_e32 v74, v74, v246
	v_add_f32_e32 v75, v75, v247
	v_fmac_f32_e32 v92, v74, v74
	v_fmac_f32_e32 v92, v75, v75
	v_cvt_pk_bf16_f32 v177, v74, v75
	global_store_dwordx4 v[238:239], v[174:177], off
	v_lshlrev_b32_e32 v246, 16, v178
	v_and_b32_e32 v247, 0xffff0000, v178
	v_add_f32_e32 v68, v68, v246
	v_add_f32_e32 v69, v69, v247
	v_fmac_f32_e32 v92, v68, v68
	v_fmac_f32_e32 v92, v69, v69
	v_cvt_pk_bf16_f32 v178, v68, v69
	v_lshlrev_b32_e32 v246, 16, v179
	v_and_b32_e32 v247, 0xffff0000, v179
	v_add_f32_e32 v70, v70, v246
	v_add_f32_e32 v71, v71, v247
	v_fmac_f32_e32 v92, v70, v70
	v_fmac_f32_e32 v92, v71, v71
	v_cvt_pk_bf16_f32 v179, v70, v71
	v_lshlrev_b32_e32 v246, 16, v180
	v_and_b32_e32 v247, 0xffff0000, v180
	v_add_f32_e32 v64, v64, v246
	v_add_f32_e32 v65, v65, v247
	v_fmac_f32_e32 v92, v64, v64
	v_fmac_f32_e32 v92, v65, v65
	v_cvt_pk_bf16_f32 v180, v64, v65
	v_lshlrev_b32_e32 v246, 16, v181
	v_and_b32_e32 v247, 0xffff0000, v181
	v_add_f32_e32 v66, v66, v246
	v_add_f32_e32 v67, v67, v247
	v_fmac_f32_e32 v92, v66, v66
	v_fmac_f32_e32 v92, v67, v67
	v_cvt_pk_bf16_f32 v181, v66, v67
	global_store_dwordx4 v[238:239], v[178:181], off offset:256
	s_waitcnt vmcnt(14)
	s_mov_b32 s100, 0x80000
	v_lshl_add_u64 v[238:239], v[236:237], 0, s[100:101]
	v_lshlrev_b32_e32 v246, 16, v184
	v_and_b32_e32 v247, 0xffff0000, v184
	v_add_f32_e32 v60, v60, v246
	v_add_f32_e32 v61, v61, v247
	v_mul_f32_e32 v76, v60, v60
	v_fmac_f32_e32 v76, v61, v61
	v_cvt_pk_bf16_f32 v184, v60, v61
	v_lshlrev_b32_e32 v246, 16, v185
	v_and_b32_e32 v247, 0xffff0000, v185
	v_add_f32_e32 v62, v62, v246
	v_add_f32_e32 v63, v63, v247
	v_fmac_f32_e32 v76, v62, v62
	v_fmac_f32_e32 v76, v63, v63
	v_cvt_pk_bf16_f32 v185, v62, v63
	v_lshlrev_b32_e32 v246, 16, v186
	v_and_b32_e32 v247, 0xffff0000, v186
	v_add_f32_e32 v56, v56, v246
	v_add_f32_e32 v57, v57, v247
	v_fmac_f32_e32 v76, v56, v56
	v_fmac_f32_e32 v76, v57, v57
	v_cvt_pk_bf16_f32 v186, v56, v57
	v_lshlrev_b32_e32 v246, 16, v187
	v_and_b32_e32 v247, 0xffff0000, v187
	v_add_f32_e32 v58, v58, v246
	v_add_f32_e32 v59, v59, v247
	v_fmac_f32_e32 v76, v58, v58
	v_fmac_f32_e32 v76, v59, v59
	v_cvt_pk_bf16_f32 v187, v58, v59
	global_store_dwordx4 v[238:239], v[184:187], off
	v_lshlrev_b32_e32 v246, 16, v188
	v_and_b32_e32 v247, 0xffff0000, v188
	v_add_f32_e32 v52, v52, v246
	v_add_f32_e32 v53, v53, v247
	v_fmac_f32_e32 v76, v52, v52
	v_fmac_f32_e32 v76, v53, v53
	v_cvt_pk_bf16_f32 v188, v52, v53
	v_lshlrev_b32_e32 v246, 16, v189
	v_and_b32_e32 v247, 0xffff0000, v189
	v_add_f32_e32 v54, v54, v246
	v_add_f32_e32 v55, v55, v247
	v_fmac_f32_e32 v76, v54, v54
	v_fmac_f32_e32 v76, v55, v55
	v_cvt_pk_bf16_f32 v189, v54, v55
	v_lshlrev_b32_e32 v246, 16, v190
	v_and_b32_e32 v247, 0xffff0000, v190
	v_add_f32_e32 v48, v48, v246
	v_add_f32_e32 v49, v49, v247
	v_fmac_f32_e32 v76, v48, v48
	v_fmac_f32_e32 v76, v49, v49
	v_cvt_pk_bf16_f32 v190, v48, v49
	v_lshlrev_b32_e32 v246, 16, v191
	v_and_b32_e32 v247, 0xffff0000, v191
	v_add_f32_e32 v50, v50, v246
	v_add_f32_e32 v51, v51, v247
	v_fmac_f32_e32 v76, v50, v50
	v_fmac_f32_e32 v76, v51, v51
	v_cvt_pk_bf16_f32 v191, v50, v51
	global_store_dwordx4 v[238:239], v[188:191], off offset:256
	s_waitcnt vmcnt(14)
	s_mov_b32 s100, 0x90000
	v_lshl_add_u64 v[238:239], v[236:237], 0, s[100:101]
	v_lshlrev_b32_e32 v246, 16, v192
	v_and_b32_e32 v247, 0xffff0000, v192
	v_add_f32_e32 v44, v44, v246
	v_add_f32_e32 v45, v45, v247
	v_mul_f32_e32 v60, v44, v44
	v_fmac_f32_e32 v60, v45, v45
	v_cvt_pk_bf16_f32 v192, v44, v45
	v_lshlrev_b32_e32 v246, 16, v193
	v_and_b32_e32 v247, 0xffff0000, v193
	v_add_f32_e32 v46, v46, v246
	v_add_f32_e32 v47, v47, v247
	v_fmac_f32_e32 v60, v46, v46
	v_fmac_f32_e32 v60, v47, v47
	v_cvt_pk_bf16_f32 v193, v46, v47
	v_lshlrev_b32_e32 v246, 16, v194
	v_and_b32_e32 v247, 0xffff0000, v194
	v_add_f32_e32 v40, v40, v246
	v_add_f32_e32 v41, v41, v247
	v_fmac_f32_e32 v60, v40, v40
	v_fmac_f32_e32 v60, v41, v41
	v_cvt_pk_bf16_f32 v194, v40, v41
	v_lshlrev_b32_e32 v246, 16, v195
	v_and_b32_e32 v247, 0xffff0000, v195
	v_add_f32_e32 v42, v42, v246
	v_add_f32_e32 v43, v43, v247
	v_fmac_f32_e32 v60, v42, v42
	v_fmac_f32_e32 v60, v43, v43
	v_cvt_pk_bf16_f32 v195, v42, v43
	global_store_dwordx4 v[238:239], v[192:195], off
	v_lshlrev_b32_e32 v246, 16, v196
	v_and_b32_e32 v247, 0xffff0000, v196
	v_add_f32_e32 v36, v36, v246
	v_add_f32_e32 v37, v37, v247
	v_fmac_f32_e32 v60, v36, v36
	v_fmac_f32_e32 v60, v37, v37
	v_cvt_pk_bf16_f32 v196, v36, v37
	v_lshlrev_b32_e32 v246, 16, v197
	v_and_b32_e32 v247, 0xffff0000, v197
	v_add_f32_e32 v38, v38, v246
	v_add_f32_e32 v39, v39, v247
	v_fmac_f32_e32 v60, v38, v38
	v_fmac_f32_e32 v60, v39, v39
	v_cvt_pk_bf16_f32 v197, v38, v39
	v_lshlrev_b32_e32 v246, 16, v198
	v_and_b32_e32 v247, 0xffff0000, v198
	v_add_f32_e32 v32, v32, v246
	v_add_f32_e32 v33, v33, v247
	v_fmac_f32_e32 v60, v32, v32
	v_fmac_f32_e32 v60, v33, v33
	v_cvt_pk_bf16_f32 v198, v32, v33
	v_lshlrev_b32_e32 v246, 16, v199
	v_and_b32_e32 v247, 0xffff0000, v199
	v_add_f32_e32 v34, v34, v246
	v_add_f32_e32 v35, v35, v247
	v_fmac_f32_e32 v60, v34, v34
	v_fmac_f32_e32 v60, v35, v35
	v_cvt_pk_bf16_f32 v199, v34, v35
	global_store_dwordx4 v[238:239], v[196:199], off offset:256
	s_waitcnt vmcnt(14)
	s_mov_b32 s100, 0xa0000
	v_lshl_add_u64 v[238:239], v[236:237], 0, s[100:101]
	v_lshlrev_b32_e32 v246, 16, v200
	v_and_b32_e32 v247, 0xffff0000, v200
	v_add_f32_e32 v28, v28, v246
	v_add_f32_e32 v29, v29, v247
	v_mul_f32_e32 v44, v28, v28
	v_fmac_f32_e32 v44, v29, v29
	v_cvt_pk_bf16_f32 v200, v28, v29
	v_lshlrev_b32_e32 v246, 16, v201
	v_and_b32_e32 v247, 0xffff0000, v201
	v_add_f32_e32 v30, v30, v246
	v_add_f32_e32 v31, v31, v247
	v_fmac_f32_e32 v44, v30, v30
	v_fmac_f32_e32 v44, v31, v31
	v_cvt_pk_bf16_f32 v201, v30, v31
	v_lshlrev_b32_e32 v246, 16, v202
	v_and_b32_e32 v247, 0xffff0000, v202
	v_add_f32_e32 v24, v24, v246
	v_add_f32_e32 v25, v25, v247
	v_fmac_f32_e32 v44, v24, v24
	v_fmac_f32_e32 v44, v25, v25
	v_cvt_pk_bf16_f32 v202, v24, v25
	v_lshlrev_b32_e32 v246, 16, v203
	v_and_b32_e32 v247, 0xffff0000, v203
	v_add_f32_e32 v26, v26, v246
	v_add_f32_e32 v27, v27, v247
	v_fmac_f32_e32 v44, v26, v26
	v_fmac_f32_e32 v44, v27, v27
	v_cvt_pk_bf16_f32 v203, v26, v27
	global_store_dwordx4 v[238:239], v[200:203], off
	v_lshlrev_b32_e32 v246, 16, v204
	v_and_b32_e32 v247, 0xffff0000, v204
	v_add_f32_e32 v20, v20, v246
	v_add_f32_e32 v21, v21, v247
	v_fmac_f32_e32 v44, v20, v20
	v_fmac_f32_e32 v44, v21, v21
	v_cvt_pk_bf16_f32 v204, v20, v21
	v_lshlrev_b32_e32 v246, 16, v205
	v_and_b32_e32 v247, 0xffff0000, v205
	v_add_f32_e32 v22, v22, v246
	v_add_f32_e32 v23, v23, v247
	v_fmac_f32_e32 v44, v22, v22
	v_fmac_f32_e32 v44, v23, v23
	v_cvt_pk_bf16_f32 v205, v22, v23
	v_lshlrev_b32_e32 v246, 16, v206
	v_and_b32_e32 v247, 0xffff0000, v206
	v_add_f32_e32 v16, v16, v246
	v_add_f32_e32 v17, v17, v247
	v_fmac_f32_e32 v44, v16, v16
	v_fmac_f32_e32 v44, v17, v17
	v_cvt_pk_bf16_f32 v206, v16, v17
	v_lshlrev_b32_e32 v246, 16, v207
	v_and_b32_e32 v247, 0xffff0000, v207
	v_add_f32_e32 v18, v18, v246
	v_add_f32_e32 v19, v19, v247
	v_fmac_f32_e32 v44, v18, v18
	v_fmac_f32_e32 v44, v19, v19
	v_cvt_pk_bf16_f32 v207, v18, v19
	global_store_dwordx4 v[238:239], v[204:207], off offset:256
	s_waitcnt vmcnt(14)
	s_mov_b32 s100, 0xb0000
	v_lshl_add_u64 v[238:239], v[236:237], 0, s[100:101]
	v_lshlrev_b32_e32 v246, 16, v208
	v_and_b32_e32 v247, 0xffff0000, v208
	v_add_f32_e32 v12, v12, v246
	v_add_f32_e32 v13, v13, v247
	v_mul_f32_e32 v28, v12, v12
	v_fmac_f32_e32 v28, v13, v13
	v_cvt_pk_bf16_f32 v208, v12, v13
	v_lshlrev_b32_e32 v246, 16, v209
	v_and_b32_e32 v247, 0xffff0000, v209
	v_add_f32_e32 v14, v14, v246
	v_add_f32_e32 v15, v15, v247
	v_fmac_f32_e32 v28, v14, v14
	v_fmac_f32_e32 v28, v15, v15
	v_cvt_pk_bf16_f32 v209, v14, v15
	v_lshlrev_b32_e32 v246, 16, v210
	v_and_b32_e32 v247, 0xffff0000, v210
	v_add_f32_e32 v8, v8, v246
	v_add_f32_e32 v9, v9, v247
	v_fmac_f32_e32 v28, v8, v8
	v_fmac_f32_e32 v28, v9, v9
	v_cvt_pk_bf16_f32 v210, v8, v9
	v_lshlrev_b32_e32 v246, 16, v211
	v_and_b32_e32 v247, 0xffff0000, v211
	v_add_f32_e32 v10, v10, v246
	v_add_f32_e32 v11, v11, v247
	v_fmac_f32_e32 v28, v10, v10
	v_fmac_f32_e32 v28, v11, v11
	v_cvt_pk_bf16_f32 v211, v10, v11
	global_store_dwordx4 v[238:239], v[208:211], off
	v_lshlrev_b32_e32 v246, 16, v212
	v_and_b32_e32 v247, 0xffff0000, v212
	v_add_f32_e32 v4, v4, v246
	v_add_f32_e32 v5, v5, v247
	v_fmac_f32_e32 v28, v4, v4
	v_fmac_f32_e32 v28, v5, v5
	v_cvt_pk_bf16_f32 v212, v4, v5
	v_lshlrev_b32_e32 v246, 16, v213
	v_and_b32_e32 v247, 0xffff0000, v213
	v_add_f32_e32 v6, v6, v246
	v_add_f32_e32 v7, v7, v247
	v_fmac_f32_e32 v28, v6, v6
	v_fmac_f32_e32 v28, v7, v7
	v_cvt_pk_bf16_f32 v213, v6, v7
	v_lshlrev_b32_e32 v246, 16, v214
	v_and_b32_e32 v247, 0xffff0000, v214
	v_add_f32_e32 v0, v0, v246
	v_add_f32_e32 v1, v1, v247
	v_fmac_f32_e32 v28, v0, v0
	v_fmac_f32_e32 v28, v1, v1
	v_cvt_pk_bf16_f32 v214, v0, v1
	v_lshlrev_b32_e32 v246, 16, v215
	v_and_b32_e32 v247, 0xffff0000, v215
	v_add_f32_e32 v2, v2, v246
	v_add_f32_e32 v3, v3, v247
	v_fmac_f32_e32 v28, v2, v2
	v_fmac_f32_e32 v28, v3, v3
	v_cvt_pk_bf16_f32 v215, v2, v3
	global_store_dwordx4 v[238:239], v[212:215], off offset:256
	ds_bpermute_b32 v0, v244, v248
	ds_bpermute_b32 v1, v244, v124
	ds_bpermute_b32 v2, v244, v108
	ds_bpermute_b32 v3, v244, v92
	ds_bpermute_b32 v8, v244, v76
	ds_bpermute_b32 v9, v244, v60
	ds_bpermute_b32 v10, v244, v44
	ds_bpermute_b32 v11, v244, v28
	s_waitcnt lgkmcnt(7)
	v_add_f32_e32 v248, v248, v0
	s_waitcnt lgkmcnt(6)
	v_add_f32_e32 v124, v124, v1
	s_waitcnt lgkmcnt(5)
	v_add_f32_e32 v108, v108, v2
	s_waitcnt lgkmcnt(4)
	v_add_f32_e32 v92, v92, v3
	s_waitcnt lgkmcnt(3)
	v_add_f32_e32 v76, v76, v8
	s_waitcnt lgkmcnt(2)
	v_add_f32_e32 v60, v60, v9
	s_waitcnt lgkmcnt(1)
	v_add_f32_e32 v44, v44, v10
	s_waitcnt lgkmcnt(0)
	v_add_f32_e32 v28, v28, v11
	ds_bpermute_b32 v0, v245, v248
	ds_bpermute_b32 v1, v245, v124
	ds_bpermute_b32 v2, v245, v108
	ds_bpermute_b32 v3, v245, v92
	ds_bpermute_b32 v8, v245, v76
	ds_bpermute_b32 v9, v245, v60
	ds_bpermute_b32 v10, v245, v44
	ds_bpermute_b32 v11, v245, v28
	s_waitcnt lgkmcnt(7)
	v_add_f32_e32 v248, v248, v0
	s_waitcnt lgkmcnt(6)
	v_add_f32_e32 v124, v124, v1
	s_waitcnt lgkmcnt(5)
	v_add_f32_e32 v108, v108, v2
	s_waitcnt lgkmcnt(4)
	v_add_f32_e32 v92, v92, v3
	s_waitcnt lgkmcnt(3)
	v_add_f32_e32 v76, v76, v8
	s_waitcnt lgkmcnt(2)
	v_add_f32_e32 v60, v60, v9
	s_waitcnt lgkmcnt(1)
	v_add_f32_e32 v44, v44, v10
	s_waitcnt lgkmcnt(0)
	v_add_f32_e32 v28, v28, v11
	s_and_saveexec_b64 s[24:25], s[6:7]
	v_lshl_add_u64 v[236:237], v[240:241], 3, s[4:5]
	v_mul_f32_e32 v248, 0x4f800000, v248
	v_trunc_f32_e32 v248, v248
	v_mul_f32_e32 v0, 0x2f800000, v248
	v_floor_f32_e32 v0, v0
	v_fmac_f32_e32 v248, 0xcf800000, v0
	v_cvt_u32_f32_e32 v246, v248
	v_cvt_u32_f32_e32 v247, v0
	global_atomic_add_x2 v[236:237], v[246:247], off
	s_nop 1
	v_mul_f32_e32 v124, 0x4f800000, v124
	v_trunc_f32_e32 v124, v124
	v_mul_f32_e32 v1, 0x2f800000, v124
	v_floor_f32_e32 v1, v1
	v_fmac_f32_e32 v124, 0xcf800000, v1
	v_cvt_u32_f32_e32 v246, v124
	v_cvt_u32_f32_e32 v247, v1
	global_atomic_add_x2 v[236:237], v[246:247], off offset:128
	s_nop 1
	v_mul_f32_e32 v108, 0x4f800000, v108
	v_trunc_f32_e32 v108, v108
	v_mul_f32_e32 v2, 0x2f800000, v108
	v_floor_f32_e32 v2, v2
	v_fmac_f32_e32 v108, 0xcf800000, v2
	v_cvt_u32_f32_e32 v246, v108
	v_cvt_u32_f32_e32 v247, v2
	global_atomic_add_x2 v[236:237], v[246:247], off offset:256
	s_nop 1
	v_mul_f32_e32 v92, 0x4f800000, v92
	v_trunc_f32_e32 v92, v92
	v_mul_f32_e32 v3, 0x2f800000, v92
	v_floor_f32_e32 v3, v3
	v_fmac_f32_e32 v92, 0xcf800000, v3
	v_cvt_u32_f32_e32 v246, v92
	v_cvt_u32_f32_e32 v247, v3
	global_atomic_add_x2 v[236:237], v[246:247], off offset:384
	s_nop 1
	v_mul_f32_e32 v76, 0x4f800000, v76
	v_trunc_f32_e32 v76, v76
	v_mul_f32_e32 v8, 0x2f800000, v76
	v_floor_f32_e32 v8, v8
	v_fmac_f32_e32 v76, 0xcf800000, v8
	v_cvt_u32_f32_e32 v246, v76
	v_cvt_u32_f32_e32 v247, v8
	global_atomic_add_x2 v[236:237], v[246:247], off offset:1024
	s_nop 1
	v_mul_f32_e32 v60, 0x4f800000, v60
	v_trunc_f32_e32 v60, v60
	v_mul_f32_e32 v9, 0x2f800000, v60
	v_floor_f32_e32 v9, v9
	v_fmac_f32_e32 v60, 0xcf800000, v9
	v_cvt_u32_f32_e32 v246, v60
	v_cvt_u32_f32_e32 v247, v9
	global_atomic_add_x2 v[236:237], v[246:247], off offset:1152
	s_nop 1
	v_mul_f32_e32 v44, 0x4f800000, v44
	v_trunc_f32_e32 v44, v44
	v_mul_f32_e32 v10, 0x2f800000, v44
	v_floor_f32_e32 v10, v10
	v_fmac_f32_e32 v44, 0xcf800000, v10
	v_cvt_u32_f32_e32 v246, v44
	v_cvt_u32_f32_e32 v247, v10
	global_atomic_add_x2 v[236:237], v[246:247], off offset:1280
	s_nop 1
	v_mul_f32_e32 v28, 0x4f800000, v28
	v_trunc_f32_e32 v28, v28
	v_mul_f32_e32 v11, 0x2f800000, v28
	v_floor_f32_e32 v11, v11
	v_fmac_f32_e32 v28, 0xcf800000, v11
	v_cvt_u32_f32_e32 v246, v28
	v_cvt_u32_f32_e32 v247, v11
	global_atomic_add_x2 v[236:237], v[246:247], off offset:1408
	s_nop 1

.LBB0_2396:
	v_lshl_add_u32 v240, s42, 8, v144
	v_and_b32_e32 v242, 0xe0, v146
	v_and_b32_e32 v243, 4, v146
	v_lshl_or_b32 v242, v243, 2, v242
	v_and_b32_e32 v243, 8, v146
	v_or_b32_e32 v242, v242, v243
	v_lshl_or_b32 v242, s43, 8, v242
	v_mov_b32_e32 v243, 0
	v_ashrrev_i32_e32 v241, 31, v240
	v_readlane_b32 s18, v234, 22
	v_readlane_b32 s19, v234, 23
	v_lshlrev_b64 v[246:247], 11, v[240:241]
	v_lshl_add_u64 v[246:247], v[246:247], 0, v[242:243]
	v_lshl_add_u64 v[236:237], v[246:247], 1, s[18:19]
	s_mov_b32 s101, 0
	global_load_dwordx4 v[140:143], v[236:237], off
	global_load_dwordx4 v[154:157], v[236:237], off offset:256
	s_mov_b32 s100, 0x10000
	v_lshl_add_u64 v[238:239], v[236:237], 0, s[100:101]
	global_load_dwordx4 v[158:161], v[238:239], off
	global_load_dwordx4 v[162:165], v[238:239], off offset:256
	s_mov_b32 s100, 0x20000
	v_lshl_add_u64 v[238:239], v[236:237], 0, s[100:101]
	global_load_dwordx4 v[166:169], v[238:239], off
	global_load_dwordx4 v[170:173], v[238:239], off offset:256
	s_mov_b32 s100, 0x30000
	v_lshl_add_u64 v[238:239], v[236:237], 0, s[100:101]
	global_load_dwordx4 v[174:177], v[238:239], off
	global_load_dwordx4 v[178:181], v[238:239], off offset:256
	s_mov_b32 s100, 0x80000
	v_lshl_add_u64 v[238:239], v[236:237], 0, s[100:101]
	global_load_dwordx4 v[184:187], v[238:239], off
	global_load_dwordx4 v[188:191], v[238:239], off offset:256
	s_mov_b32 s100, 0x90000
	v_lshl_add_u64 v[238:239], v[236:237], 0, s[100:101]
	global_load_dwordx4 v[192:195], v[238:239], off
	global_load_dwordx4 v[196:199], v[238:239], off offset:256
	s_mov_b32 s100, 0xa0000
	v_lshl_add_u64 v[238:239], v[236:237], 0, s[100:101]
	global_load_dwordx4 v[200:203], v[238:239], off
	global_load_dwordx4 v[204:207], v[238:239], off offset:256
	s_mov_b32 s100, 0xb0000
	v_lshl_add_u64 v[238:239], v[236:237], 0, s[100:101]
	global_load_dwordx4 v[208:211], v[238:239], off
	global_load_dwordx4 v[212:215], v[238:239], off offset:256
	v_lshlrev_b32_e32 v244, 2, v150
	v_lshlrev_b32_e32 v245, 2, v151
	v_permlane16_swap_b32_e32 v124, v120
	v_permlane16_swap_b32_e32 v125, v121
	v_permlane16_swap_b32_e32 v126, v122
	v_permlane16_swap_b32_e32 v127, v123
	v_permlane16_swap_b32_e32 v116, v112
	v_permlane16_swap_b32_e32 v117, v113
	v_permlane16_swap_b32_e32 v118, v114
	v_permlane16_swap_b32_e32 v119, v115
	v_permlane16_swap_b32_e32 v108, v104
	v_permlane16_swap_b32_e32 v109, v105
	v_permlane16_swap_b32_e32 v110, v106
	v_permlane16_swap_b32_e32 v111, v107
	v_permlane16_swap_b32_e32 v100, v96
	v_permlane16_swap_b32_e32 v101, v97
	v_permlane16_swap_b32_e32 v102, v98
	v_permlane16_swap_b32_e32 v103, v99
	v_permlane16_swap_b32_e32 v92, v88
	v_permlane16_swap_b32_e32 v93, v89
	v_permlane16_swap_b32_e32 v94, v90
	v_permlane16_swap_b32_e32 v95, v91
	v_permlane16_swap_b32_e32 v84, v80
	v_permlane16_swap_b32_e32 v85, v81
	v_permlane16_swap_b32_e32 v86, v82
	v_permlane16_swap_b32_e32 v87, v83
	v_permlane16_swap_b32_e32 v76, v72
	v_permlane16_swap_b32_e32 v77, v73
	v_permlane16_swap_b32_e32 v78, v74
	v_permlane16_swap_b32_e32 v79, v75
	v_permlane16_swap_b32_e32 v68, v64
	v_permlane16_swap_b32_e32 v69, v65
	v_permlane16_swap_b32_e32 v70, v66
	v_permlane16_swap_b32_e32 v71, v67
	v_permlane16_swap_b32_e32 v60, v56
	v_permlane16_swap_b32_e32 v61, v57
	v_permlane16_swap_b32_e32 v62, v58
	v_permlane16_swap_b32_e32 v63, v59
	v_permlane16_swap_b32_e32 v52, v48
	v_permlane16_swap_b32_e32 v53, v49
	v_permlane16_swap_b32_e32 v54, v50
	v_permlane16_swap_b32_e32 v55, v51
	v_permlane16_swap_b32_e32 v44, v40
	v_permlane16_swap_b32_e32 v45, v41
	v_permlane16_swap_b32_e32 v46, v42
	v_permlane16_swap_b32_e32 v47, v43
	v_permlane16_swap_b32_e32 v36, v32
	v_permlane16_swap_b32_e32 v37, v33
	v_permlane16_swap_b32_e32 v38, v34
	v_permlane16_swap_b32_e32 v39, v35
	v_permlane16_swap_b32_e32 v28, v24
	v_permlane16_swap_b32_e32 v29, v25
	v_permlane16_swap_b32_e32 v30, v26
	v_permlane16_swap_b32_e32 v31, v27
	v_permlane16_swap_b32_e32 v20, v16
	v_permlane16_swap_b32_e32 v21, v17
	v_permlane16_swap_b32_e32 v22, v18
	v_permlane16_swap_b32_e32 v23, v19
	v_permlane16_swap_b32_e32 v12, v8
	v_permlane16_swap_b32_e32 v13, v9
	v_permlane16_swap_b32_e32 v14, v10
	v_permlane16_swap_b32_e32 v15, v11
	v_permlane16_swap_b32_e32 v4, v0
	v_permlane16_swap_b32_e32 v5, v1
	v_permlane16_swap_b32_e32 v6, v2
	v_permlane16_swap_b32_e32 v7, v3
	s_waitcnt vmcnt(14)
	v_lshlrev_b32_e32 v246, 16, v140
	v_and_b32_e32 v247, 0xffff0000, v140
	v_fma_f32 v124, v124, 0.5, v246
	v_fma_f32 v125, v125, 0.5, v247
	v_mul_f32_e32 v248, v124, v124
	v_fmac_f32_e32 v248, v125, v125
	v_cvt_pk_bf16_f32 v140, v124, v125
	v_lshlrev_b32_e32 v246, 16, v141
	v_and_b32_e32 v247, 0xffff0000, v141
	v_fma_f32 v126, v126, 0.5, v246
	v_fma_f32 v127, v127, 0.5, v247
	v_fmac_f32_e32 v248, v126, v126
	v_fmac_f32_e32 v248, v127, v127
	v_cvt_pk_bf16_f32 v141, v126, v127
	v_lshlrev_b32_e32 v246, 16, v142
	v_and_b32_e32 v247, 0xffff0000, v142
	v_fma_f32 v120, v120, 0.5, v246
	v_fma_f32 v121, v121, 0.5, v247
	v_fmac_f32_e32 v248, v120, v120
	v_fmac_f32_e32 v248, v121, v121
	v_cvt_pk_bf16_f32 v142, v120, v121
	v_lshlrev_b32_e32 v246, 16, v143
	v_and_b32_e32 v247, 0xffff0000, v143
	v_fma_f32 v122, v122, 0.5, v246
	v_fma_f32 v123, v123, 0.5, v247
	v_fmac_f32_e32 v248, v122, v122
	v_fmac_f32_e32 v248, v123, v123
	v_cvt_pk_bf16_f32 v143, v122, v123
	global_store_dwordx4 v[236:237], v[140:143], off
	v_lshlrev_b32_e32 v246, 16, v154
	v_and_b32_e32 v247, 0xffff0000, v154
	v_fma_f32 v116, v116, 0.5, v246
	v_fma_f32 v117, v117, 0.5, v247
	v_fmac_f32_e32 v248, v116, v116
	v_fmac_f32_e32 v248, v117, v117
	v_cvt_pk_bf16_f32 v154, v116, v117
	v_lshlrev_b32_e32 v246, 16, v155
	v_and_b32_e32 v247, 0xffff0000, v155
	v_fma_f32 v118, v118, 0.5, v246
	v_fma_f32 v119, v119, 0.5, v247
	v_fmac_f32_e32 v248, v118, v118
	v_fmac_f32_e32 v248, v119, v119
	v_cvt_pk_bf16_f32 v155, v118, v119
	v_lshlrev_b32_e32 v246, 16, v156
	v_and_b32_e32 v247, 0xffff0000, v156
	v_fma_f32 v112, v112, 0.5, v246
	v_fma_f32 v113, v113, 0.5, v247
	v_fmac_f32_e32 v248, v112, v112
	v_fmac_f32_e32 v248, v113, v113
	v_cvt_pk_bf16_f32 v156, v112, v113
	v_lshlrev_b32_e32 v246, 16, v157
	v_and_b32_e32 v247, 0xffff0000, v157
	v_fma_f32 v114, v114, 0.5, v246
	v_fma_f32 v115, v115, 0.5, v247
	v_fmac_f32_e32 v248, v114, v114
	v_fmac_f32_e32 v248, v115, v115
	v_cvt_pk_bf16_f32 v157, v114, v115
	global_store_dwordx4 v[236:237], v[154:157], off offset:256
	s_waitcnt vmcnt(14)
	s_mov_b32 s100, 0x10000
	v_lshl_add_u64 v[238:239], v[236:237], 0, s[100:101]
	v_lshlrev_b32_e32 v246, 16, v158
	v_and_b32_e32 v247, 0xffff0000, v158
	v_fma_f32 v108, v108, 0.5, v246
	v_fma_f32 v109, v109, 0.5, v247
	v_mul_f32_e32 v124, v108, v108
	v_fmac_f32_e32 v124, v109, v109
	v_cvt_pk_bf16_f32 v158, v108, v109
	v_lshlrev_b32_e32 v246, 16, v159
	v_and_b32_e32 v247, 0xffff0000, v159
	v_fma_f32 v110, v110, 0.5, v246
	v_fma_f32 v111, v111, 0.5, v247
	v_fmac_f32_e32 v124, v110, v110
	v_fmac_f32_e32 v124, v111, v111
	v_cvt_pk_bf16_f32 v159, v110, v111
	v_lshlrev_b32_e32 v246, 16, v160
	v_and_b32_e32 v247, 0xffff0000, v160
	v_fma_f32 v104, v104, 0.5, v246
	v_fma_f32 v105, v105, 0.5, v247
	v_fmac_f32_e32 v124, v104, v104
	v_fmac_f32_e32 v124, v105, v105
	v_cvt_pk_bf16_f32 v160, v104, v105
	v_lshlrev_b32_e32 v246, 16, v161
	v_and_b32_e32 v247, 0xffff0000, v161
	v_fma_f32 v106, v106, 0.5, v246
	v_fma_f32 v107, v107, 0.5, v247
	v_fmac_f32_e32 v124, v106, v106
	v_fmac_f32_e32 v124, v107, v107
	v_cvt_pk_bf16_f32 v161, v106, v107
	global_store_dwordx4 v[238:239], v[158:161], off
	v_lshlrev_b32_e32 v246, 16, v162
	v_and_b32_e32 v247, 0xffff0000, v162
	v_fma_f32 v100, v100, 0.5, v246
	v_fma_f32 v101, v101, 0.5, v247
	v_fmac_f32_e32 v124, v100, v100
	v_fmac_f32_e32 v124, v101, v101
	v_cvt_pk_bf16_f32 v162, v100, v101
	v_lshlrev_b32_e32 v246, 16, v163
	v_and_b32_e32 v247, 0xffff0000, v163
	v_fma_f32 v102, v102, 0.5, v246
	v_fma_f32 v103, v103, 0.5, v247
	v_fmac_f32_e32 v124, v102, v102
	v_fmac_f32_e32 v124, v103, v103
	v_cvt_pk_bf16_f32 v163, v102, v103
	v_lshlrev_b32_e32 v246, 16, v164
	v_and_b32_e32 v247, 0xffff0000, v164
	v_fma_f32 v96, v96, 0.5, v246
	v_fma_f32 v97, v97, 0.5, v247
	v_fmac_f32_e32 v124, v96, v96
	v_fmac_f32_e32 v124, v97, v97
	v_cvt_pk_bf16_f32 v164, v96, v97
	v_lshlrev_b32_e32 v246, 16, v165
	v_and_b32_e32 v247, 0xffff0000, v165
	v_fma_f32 v98, v98, 0.5, v246
	v_fma_f32 v99, v99, 0.5, v247
	v_fmac_f32_e32 v124, v98, v98
	v_fmac_f32_e32 v124, v99, v99
	v_cvt_pk_bf16_f32 v165, v98, v99
	global_store_dwordx4 v[238:239], v[162:165], off offset:256
	s_waitcnt vmcnt(14)
	s_mov_b32 s100, 0x20000
	v_lshl_add_u64 v[238:239], v[236:237], 0, s[100:101]
	v_lshlrev_b32_e32 v246, 16, v166
	v_and_b32_e32 v247, 0xffff0000, v166
	v_fma_f32 v92, v92, 0.5, v246
	v_fma_f32 v93, v93, 0.5, v247
	v_mul_f32_e32 v108, v92, v92
	v_fmac_f32_e32 v108, v93, v93
	v_cvt_pk_bf16_f32 v166, v92, v93
	v_lshlrev_b32_e32 v246, 16, v167
	v_and_b32_e32 v247, 0xffff0000, v167
	v_fma_f32 v94, v94, 0.5, v246
	v_fma_f32 v95, v95, 0.5, v247
	v_fmac_f32_e32 v108, v94, v94
	v_fmac_f32_e32 v108, v95, v95
	v_cvt_pk_bf16_f32 v167, v94, v95
	v_lshlrev_b32_e32 v246, 16, v168
	v_and_b32_e32 v247, 0xffff0000, v168
	v_fma_f32 v88, v88, 0.5, v246
	v_fma_f32 v89, v89, 0.5, v247
	v_fmac_f32_e32 v108, v88, v88
	v_fmac_f32_e32 v108, v89, v89
	v_cvt_pk_bf16_f32 v168, v88, v89
	v_lshlrev_b32_e32 v246, 16, v169
	v_and_b32_e32 v247, 0xffff0000, v169
	v_fma_f32 v90, v90, 0.5, v246
	v_fma_f32 v91, v91, 0.5, v247
	v_fmac_f32_e32 v108, v90, v90
	v_fmac_f32_e32 v108, v91, v91
	v_cvt_pk_bf16_f32 v169, v90, v91
	global_store_dwordx4 v[238:239], v[166:169], off
	v_lshlrev_b32_e32 v246, 16, v170
	v_and_b32_e32 v247, 0xffff0000, v170
	v_fma_f32 v84, v84, 0.5, v246
	v_fma_f32 v85, v85, 0.5, v247
	v_fmac_f32_e32 v108, v84, v84
	v_fmac_f32_e32 v108, v85, v85
	v_cvt_pk_bf16_f32 v170, v84, v85
	v_lshlrev_b32_e32 v246, 16, v171
	v_and_b32_e32 v247, 0xffff0000, v171
	v_fma_f32 v86, v86, 0.5, v246
	v_fma_f32 v87, v87, 0.5, v247
	v_fmac_f32_e32 v108, v86, v86
	v_fmac_f32_e32 v108, v87, v87
	v_cvt_pk_bf16_f32 v171, v86, v87
	v_lshlrev_b32_e32 v246, 16, v172
	v_and_b32_e32 v247, 0xffff0000, v172
	v_fma_f32 v80, v80, 0.5, v246
	v_fma_f32 v81, v81, 0.5, v247
	v_fmac_f32_e32 v108, v80, v80
	v_fmac_f32_e32 v108, v81, v81
	v_cvt_pk_bf16_f32 v172, v80, v81
	v_lshlrev_b32_e32 v246, 16, v173
	v_and_b32_e32 v247, 0xffff0000, v173
	v_fma_f32 v82, v82, 0.5, v246
	v_fma_f32 v83, v83, 0.5, v247
	v_fmac_f32_e32 v108, v82, v82
	v_fmac_f32_e32 v108, v83, v83
	v_cvt_pk_bf16_f32 v173, v82, v83
	global_store_dwordx4 v[238:239], v[170:173], off offset:256
	s_waitcnt vmcnt(14)
	s_mov_b32 s100, 0x30000
	v_lshl_add_u64 v[238:239], v[236:237], 0, s[100:101]
	v_lshlrev_b32_e32 v246, 16, v174
	v_and_b32_e32 v247, 0xffff0000, v174
	v_fma_f32 v76, v76, 0.5, v246
	v_fma_f32 v77, v77, 0.5, v247
	v_mul_f32_e32 v92, v76, v76
	v_fmac_f32_e32 v92, v77, v77
	v_cvt_pk_bf16_f32 v174, v76, v77
	v_lshlrev_b32_e32 v246, 16, v175
	v_and_b32_e32 v247, 0xffff0000, v175
	v_fma_f32 v78, v78, 0.5, v246
	v_fma_f32 v79, v79, 0.5, v247
	v_fmac_f32_e32 v92, v78, v78
	v_fmac_f32_e32 v92, v79, v79
	v_cvt_pk_bf16_f32 v175, v78, v79
	v_lshlrev_b32_e32 v246, 16, v176
	v_and_b32_e32 v247, 0xffff0000, v176
	v_fma_f32 v72, v72, 0.5, v246
	v_fma_f32 v73, v73, 0.5, v247
	v_fmac_f32_e32 v92, v72, v72
	v_fmac_f32_e32 v92, v73, v73
	v_cvt_pk_bf16_f32 v176, v72, v73
	v_lshlrev_b32_e32 v246, 16, v177
	v_and_b32_e32 v247, 0xffff0000, v177
	v_fma_f32 v74, v74, 0.5, v246
	v_fma_f32 v75, v75, 0.5, v247
	v_fmac_f32_e32 v92, v74, v74
	v_fmac_f32_e32 v92, v75, v75
	v_cvt_pk_bf16_f32 v177, v74, v75
	global_store_dwordx4 v[238:239], v[174:177], off
	v_lshlrev_b32_e32 v246, 16, v178
	v_and_b32_e32 v247, 0xffff0000, v178
	v_fma_f32 v68, v68, 0.5, v246
	v_fma_f32 v69, v69, 0.5, v247
	v_fmac_f32_e32 v92, v68, v68
	v_fmac_f32_e32 v92, v69, v69
	v_cvt_pk_bf16_f32 v178, v68, v69
	v_lshlrev_b32_e32 v246, 16, v179
	v_and_b32_e32 v247, 0xffff0000, v179
	v_fma_f32 v70, v70, 0.5, v246
	v_fma_f32 v71, v71, 0.5, v247
	v_fmac_f32_e32 v92, v70, v70
	v_fmac_f32_e32 v92, v71, v71
	v_cvt_pk_bf16_f32 v179, v70, v71
	v_lshlrev_b32_e32 v246, 16, v180
	v_and_b32_e32 v247, 0xffff0000, v180
	v_fma_f32 v64, v64, 0.5, v246
	v_fma_f32 v65, v65, 0.5, v247
	v_fmac_f32_e32 v92, v64, v64
	v_fmac_f32_e32 v92, v65, v65
	v_cvt_pk_bf16_f32 v180, v64, v65
	v_lshlrev_b32_e32 v246, 16, v181
	v_and_b32_e32 v247, 0xffff0000, v181
	v_fma_f32 v66, v66, 0.5, v246
	v_fma_f32 v67, v67, 0.5, v247
	v_fmac_f32_e32 v92, v66, v66
	v_fmac_f32_e32 v92, v67, v67
	v_cvt_pk_bf16_f32 v181, v66, v67
	global_store_dwordx4 v[238:239], v[178:181], off offset:256
	s_waitcnt vmcnt(14)
	s_mov_b32 s100, 0x80000
	v_lshl_add_u64 v[238:239], v[236:237], 0, s[100:101]
	v_lshlrev_b32_e32 v246, 16, v184
	v_and_b32_e32 v247, 0xffff0000, v184
	v_fma_f32 v60, v60, 0.5, v246
	v_fma_f32 v61, v61, 0.5, v247
	v_mul_f32_e32 v76, v60, v60
	v_fmac_f32_e32 v76, v61, v61
	v_cvt_pk_bf16_f32 v184, v60, v61
	v_lshlrev_b32_e32 v246, 16, v185
	v_and_b32_e32 v247, 0xffff0000, v185
	v_fma_f32 v62, v62, 0.5, v246
	v_fma_f32 v63, v63, 0.5, v247
	v_fmac_f32_e32 v76, v62, v62
	v_fmac_f32_e32 v76, v63, v63
	v_cvt_pk_bf16_f32 v185, v62, v63
	v_lshlrev_b32_e32 v246, 16, v186
	v_and_b32_e32 v247, 0xffff0000, v186
	v_fma_f32 v56, v56, 0.5, v246
	v_fma_f32 v57, v57, 0.5, v247
	v_fmac_f32_e32 v76, v56, v56
	v_fmac_f32_e32 v76, v57, v57
	v_cvt_pk_bf16_f32 v186, v56, v57
	v_lshlrev_b32_e32 v246, 16, v187
	v_and_b32_e32 v247, 0xffff0000, v187
	v_fma_f32 v58, v58, 0.5, v246
	v_fma_f32 v59, v59, 0.5, v247
	v_fmac_f32_e32 v76, v58, v58
	v_fmac_f32_e32 v76, v59, v59
	v_cvt_pk_bf16_f32 v187, v58, v59
	global_store_dwordx4 v[238:239], v[184:187], off
	v_lshlrev_b32_e32 v246, 16, v188
	v_and_b32_e32 v247, 0xffff0000, v188
	v_fma_f32 v52, v52, 0.5, v246
	v_fma_f32 v53, v53, 0.5, v247
	v_fmac_f32_e32 v76, v52, v52
	v_fmac_f32_e32 v76, v53, v53
	v_cvt_pk_bf16_f32 v188, v52, v53
	v_lshlrev_b32_e32 v246, 16, v189
	v_and_b32_e32 v247, 0xffff0000, v189
	v_fma_f32 v54, v54, 0.5, v246
	v_fma_f32 v55, v55, 0.5, v247
	v_fmac_f32_e32 v76, v54, v54
	v_fmac_f32_e32 v76, v55, v55
	v_cvt_pk_bf16_f32 v189, v54, v55
	v_lshlrev_b32_e32 v246, 16, v190
	v_and_b32_e32 v247, 0xffff0000, v190
	v_fma_f32 v48, v48, 0.5, v246
	v_fma_f32 v49, v49, 0.5, v247
	v_fmac_f32_e32 v76, v48, v48
	v_fmac_f32_e32 v76, v49, v49
	v_cvt_pk_bf16_f32 v190, v48, v49
	v_lshlrev_b32_e32 v246, 16, v191
	v_and_b32_e32 v247, 0xffff0000, v191
	v_fma_f32 v50, v50, 0.5, v246
	v_fma_f32 v51, v51, 0.5, v247
	v_fmac_f32_e32 v76, v50, v50
	v_fmac_f32_e32 v76, v51, v51
	v_cvt_pk_bf16_f32 v191, v50, v51
	global_store_dwordx4 v[238:239], v[188:191], off offset:256
	s_waitcnt vmcnt(14)
	s_mov_b32 s100, 0x90000
	v_lshl_add_u64 v[238:239], v[236:237], 0, s[100:101]
	v_lshlrev_b32_e32 v246, 16, v192
	v_and_b32_e32 v247, 0xffff0000, v192
	v_fma_f32 v44, v44, 0.5, v246
	v_fma_f32 v45, v45, 0.5, v247
	v_mul_f32_e32 v60, v44, v44
	v_fmac_f32_e32 v60, v45, v45
	v_cvt_pk_bf16_f32 v192, v44, v45
	v_lshlrev_b32_e32 v246, 16, v193
	v_and_b32_e32 v247, 0xffff0000, v193
	v_fma_f32 v46, v46, 0.5, v246
	v_fma_f32 v47, v47, 0.5, v247
	v_fmac_f32_e32 v60, v46, v46
	v_fmac_f32_e32 v60, v47, v47
	v_cvt_pk_bf16_f32 v193, v46, v47
	v_lshlrev_b32_e32 v246, 16, v194
	v_and_b32_e32 v247, 0xffff0000, v194
	v_fma_f32 v40, v40, 0.5, v246
	v_fma_f32 v41, v41, 0.5, v247
	v_fmac_f32_e32 v60, v40, v40
	v_fmac_f32_e32 v60, v41, v41
	v_cvt_pk_bf16_f32 v194, v40, v41
	v_lshlrev_b32_e32 v246, 16, v195
	v_and_b32_e32 v247, 0xffff0000, v195
	v_fma_f32 v42, v42, 0.5, v246
	v_fma_f32 v43, v43, 0.5, v247
	v_fmac_f32_e32 v60, v42, v42
	v_fmac_f32_e32 v60, v43, v43
	v_cvt_pk_bf16_f32 v195, v42, v43
	global_store_dwordx4 v[238:239], v[192:195], off
	v_lshlrev_b32_e32 v246, 16, v196
	v_and_b32_e32 v247, 0xffff0000, v196
	v_fma_f32 v36, v36, 0.5, v246
	v_fma_f32 v37, v37, 0.5, v247
	v_fmac_f32_e32 v60, v36, v36
	v_fmac_f32_e32 v60, v37, v37
	v_cvt_pk_bf16_f32 v196, v36, v37
	v_lshlrev_b32_e32 v246, 16, v197
	v_and_b32_e32 v247, 0xffff0000, v197
	v_fma_f32 v38, v38, 0.5, v246
	v_fma_f32 v39, v39, 0.5, v247
	v_fmac_f32_e32 v60, v38, v38
	v_fmac_f32_e32 v60, v39, v39
	v_cvt_pk_bf16_f32 v197, v38, v39
	v_lshlrev_b32_e32 v246, 16, v198
	v_and_b32_e32 v247, 0xffff0000, v198
	v_fma_f32 v32, v32, 0.5, v246
	v_fma_f32 v33, v33, 0.5, v247
	v_fmac_f32_e32 v60, v32, v32
	v_fmac_f32_e32 v60, v33, v33
	v_cvt_pk_bf16_f32 v198, v32, v33
	v_lshlrev_b32_e32 v246, 16, v199
	v_and_b32_e32 v247, 0xffff0000, v199
	v_fma_f32 v34, v34, 0.5, v246
	v_fma_f32 v35, v35, 0.5, v247
	v_fmac_f32_e32 v60, v34, v34
	v_fmac_f32_e32 v60, v35, v35
	v_cvt_pk_bf16_f32 v199, v34, v35
	global_store_dwordx4 v[238:239], v[196:199], off offset:256
	s_waitcnt vmcnt(14)
	s_mov_b32 s100, 0xa0000
	v_lshl_add_u64 v[238:239], v[236:237], 0, s[100:101]
	v_lshlrev_b32_e32 v246, 16, v200
	v_and_b32_e32 v247, 0xffff0000, v200
	v_fma_f32 v28, v28, 0.5, v246
	v_fma_f32 v29, v29, 0.5, v247
	v_mul_f32_e32 v44, v28, v28
	v_fmac_f32_e32 v44, v29, v29
	v_cvt_pk_bf16_f32 v200, v28, v29
	v_lshlrev_b32_e32 v246, 16, v201
	v_and_b32_e32 v247, 0xffff0000, v201
	v_fma_f32 v30, v30, 0.5, v246
	v_fma_f32 v31, v31, 0.5, v247
	v_fmac_f32_e32 v44, v30, v30
	v_fmac_f32_e32 v44, v31, v31
	v_cvt_pk_bf16_f32 v201, v30, v31
	v_lshlrev_b32_e32 v246, 16, v202
	v_and_b32_e32 v247, 0xffff0000, v202
	v_fma_f32 v24, v24, 0.5, v246
	v_fma_f32 v25, v25, 0.5, v247
	v_fmac_f32_e32 v44, v24, v24
	v_fmac_f32_e32 v44, v25, v25
	v_cvt_pk_bf16_f32 v202, v24, v25
	v_lshlrev_b32_e32 v246, 16, v203
	v_and_b32_e32 v247, 0xffff0000, v203
	v_fma_f32 v26, v26, 0.5, v246
	v_fma_f32 v27, v27, 0.5, v247
	v_fmac_f32_e32 v44, v26, v26
	v_fmac_f32_e32 v44, v27, v27
	v_cvt_pk_bf16_f32 v203, v26, v27
	global_store_dwordx4 v[238:239], v[200:203], off
	v_lshlrev_b32_e32 v246, 16, v204
	v_and_b32_e32 v247, 0xffff0000, v204
	v_fma_f32 v20, v20, 0.5, v246
	v_fma_f32 v21, v21, 0.5, v247
	v_fmac_f32_e32 v44, v20, v20
	v_fmac_f32_e32 v44, v21, v21
	v_cvt_pk_bf16_f32 v204, v20, v21
	v_lshlrev_b32_e32 v246, 16, v205
	v_and_b32_e32 v247, 0xffff0000, v205
	v_fma_f32 v22, v22, 0.5, v246
	v_fma_f32 v23, v23, 0.5, v247
	v_fmac_f32_e32 v44, v22, v22
	v_fmac_f32_e32 v44, v23, v23
	v_cvt_pk_bf16_f32 v205, v22, v23
	v_lshlrev_b32_e32 v246, 16, v206
	v_and_b32_e32 v247, 0xffff0000, v206
	v_fma_f32 v16, v16, 0.5, v246
	v_fma_f32 v17, v17, 0.5, v247
	v_fmac_f32_e32 v44, v16, v16
	v_fmac_f32_e32 v44, v17, v17
	v_cvt_pk_bf16_f32 v206, v16, v17
	v_lshlrev_b32_e32 v246, 16, v207
	v_and_b32_e32 v247, 0xffff0000, v207
	v_fma_f32 v18, v18, 0.5, v246
	v_fma_f32 v19, v19, 0.5, v247
	v_fmac_f32_e32 v44, v18, v18
	v_fmac_f32_e32 v44, v19, v19
	v_cvt_pk_bf16_f32 v207, v18, v19
	global_store_dwordx4 v[238:239], v[204:207], off offset:256
	s_waitcnt vmcnt(14)
	s_mov_b32 s100, 0xb0000
	v_lshl_add_u64 v[238:239], v[236:237], 0, s[100:101]
	v_lshlrev_b32_e32 v246, 16, v208
	v_and_b32_e32 v247, 0xffff0000, v208
	v_fma_f32 v12, v12, 0.5, v246
	v_fma_f32 v13, v13, 0.5, v247
	v_mul_f32_e32 v28, v12, v12
	v_fmac_f32_e32 v28, v13, v13
	v_cvt_pk_bf16_f32 v208, v12, v13
	v_lshlrev_b32_e32 v246, 16, v209
	v_and_b32_e32 v247, 0xffff0000, v209
	v_fma_f32 v14, v14, 0.5, v246
	v_fma_f32 v15, v15, 0.5, v247
	v_fmac_f32_e32 v28, v14, v14
	v_fmac_f32_e32 v28, v15, v15
	v_cvt_pk_bf16_f32 v209, v14, v15
	v_lshlrev_b32_e32 v246, 16, v210
	v_and_b32_e32 v247, 0xffff0000, v210
	v_fma_f32 v8, v8, 0.5, v246
	v_fma_f32 v9, v9, 0.5, v247
	v_fmac_f32_e32 v28, v8, v8
	v_fmac_f32_e32 v28, v9, v9
	v_cvt_pk_bf16_f32 v210, v8, v9
	v_lshlrev_b32_e32 v246, 16, v211
	v_and_b32_e32 v247, 0xffff0000, v211
	v_fma_f32 v10, v10, 0.5, v246
	v_fma_f32 v11, v11, 0.5, v247
	v_fmac_f32_e32 v28, v10, v10
	v_fmac_f32_e32 v28, v11, v11
	v_cvt_pk_bf16_f32 v211, v10, v11
	global_store_dwordx4 v[238:239], v[208:211], off
	v_lshlrev_b32_e32 v246, 16, v212
	v_and_b32_e32 v247, 0xffff0000, v212
	v_fma_f32 v4, v4, 0.5, v246
	v_fma_f32 v5, v5, 0.5, v247
	v_fmac_f32_e32 v28, v4, v4
	v_fmac_f32_e32 v28, v5, v5
	v_cvt_pk_bf16_f32 v212, v4, v5
	v_lshlrev_b32_e32 v246, 16, v213
	v_and_b32_e32 v247, 0xffff0000, v213
	v_fma_f32 v6, v6, 0.5, v246
	v_fma_f32 v7, v7, 0.5, v247
	v_fmac_f32_e32 v28, v6, v6
	v_fmac_f32_e32 v28, v7, v7
	v_cvt_pk_bf16_f32 v213, v6, v7
	v_lshlrev_b32_e32 v246, 16, v214
	v_and_b32_e32 v247, 0xffff0000, v214
	v_fma_f32 v0, v0, 0.5, v246
	v_fma_f32 v1, v1, 0.5, v247
	v_fmac_f32_e32 v28, v0, v0
	v_fmac_f32_e32 v28, v1, v1
	v_cvt_pk_bf16_f32 v214, v0, v1
	v_lshlrev_b32_e32 v246, 16, v215
	v_and_b32_e32 v247, 0xffff0000, v215
	v_fma_f32 v2, v2, 0.5, v246
	v_fma_f32 v3, v3, 0.5, v247
	v_fmac_f32_e32 v28, v2, v2
	v_fmac_f32_e32 v28, v3, v3
	v_cvt_pk_bf16_f32 v215, v2, v3
	global_store_dwordx4 v[238:239], v[212:215], off offset:256
	ds_bpermute_b32 v0, v244, v248
	ds_bpermute_b32 v1, v244, v124
	ds_bpermute_b32 v2, v244, v108
	ds_bpermute_b32 v3, v244, v92
	ds_bpermute_b32 v8, v244, v76
	ds_bpermute_b32 v9, v244, v60
	ds_bpermute_b32 v10, v244, v44
	ds_bpermute_b32 v11, v244, v28
	s_waitcnt lgkmcnt(7)
	v_add_f32_e32 v248, v248, v0
	s_waitcnt lgkmcnt(6)
	v_add_f32_e32 v124, v124, v1
	s_waitcnt lgkmcnt(5)
	v_add_f32_e32 v108, v108, v2
	s_waitcnt lgkmcnt(4)
	v_add_f32_e32 v92, v92, v3
	s_waitcnt lgkmcnt(3)
	v_add_f32_e32 v76, v76, v8
	s_waitcnt lgkmcnt(2)
	v_add_f32_e32 v60, v60, v9
	s_waitcnt lgkmcnt(1)
	v_add_f32_e32 v44, v44, v10
	s_waitcnt lgkmcnt(0)
	v_add_f32_e32 v28, v28, v11
	ds_bpermute_b32 v0, v245, v248
	ds_bpermute_b32 v1, v245, v124
	ds_bpermute_b32 v2, v245, v108
	ds_bpermute_b32 v3, v245, v92
	ds_bpermute_b32 v8, v245, v76
	ds_bpermute_b32 v9, v245, v60
	ds_bpermute_b32 v10, v245, v44
	ds_bpermute_b32 v11, v245, v28
	s_waitcnt lgkmcnt(7)
	v_add_f32_e32 v248, v248, v0
	s_waitcnt lgkmcnt(6)
	v_add_f32_e32 v124, v124, v1
	s_waitcnt lgkmcnt(5)
	v_add_f32_e32 v108, v108, v2
	s_waitcnt lgkmcnt(4)
	v_add_f32_e32 v92, v92, v3
	s_waitcnt lgkmcnt(3)
	v_add_f32_e32 v76, v76, v8
	s_waitcnt lgkmcnt(2)
	v_add_f32_e32 v60, v60, v9
	s_waitcnt lgkmcnt(1)
	v_add_f32_e32 v44, v44, v10
	s_waitcnt lgkmcnt(0)
	v_add_f32_e32 v28, v28, v11
	s_and_saveexec_b64 s[18:19], s[8:9]
	v_lshl_add_u64 v[236:237], v[240:241], 3, s[10:11]
	v_mul_f32_e32 v248, 0x4f800000, v248
	v_trunc_f32_e32 v248, v248
	v_mul_f32_e32 v0, 0x2f800000, v248
	v_floor_f32_e32 v0, v0
	v_fmac_f32_e32 v248, 0xcf800000, v0
	v_cvt_u32_f32_e32 v246, v248
	v_cvt_u32_f32_e32 v247, v0
	global_atomic_add_x2 v[236:237], v[246:247], off
	s_nop 1
	v_mul_f32_e32 v124, 0x4f800000, v124
	v_trunc_f32_e32 v124, v124
	v_mul_f32_e32 v1, 0x2f800000, v124
	v_floor_f32_e32 v1, v1
	v_fmac_f32_e32 v124, 0xcf800000, v1
	v_cvt_u32_f32_e32 v246, v124
	v_cvt_u32_f32_e32 v247, v1
	global_atomic_add_x2 v[236:237], v[246:247], off offset:128
	s_nop 1
	v_mul_f32_e32 v108, 0x4f800000, v108
	v_trunc_f32_e32 v108, v108
	v_mul_f32_e32 v2, 0x2f800000, v108
	v_floor_f32_e32 v2, v2
	v_fmac_f32_e32 v108, 0xcf800000, v2
	v_cvt_u32_f32_e32 v246, v108
	v_cvt_u32_f32_e32 v247, v2
	global_atomic_add_x2 v[236:237], v[246:247], off offset:256
	s_nop 1
	v_mul_f32_e32 v92, 0x4f800000, v92
	v_trunc_f32_e32 v92, v92
	v_mul_f32_e32 v3, 0x2f800000, v92
	v_floor_f32_e32 v3, v3
	v_fmac_f32_e32 v92, 0xcf800000, v3
	v_cvt_u32_f32_e32 v246, v92
	v_cvt_u32_f32_e32 v247, v3
	global_atomic_add_x2 v[236:237], v[246:247], off offset:384
	s_nop 1
	v_mul_f32_e32 v76, 0x4f800000, v76
	v_trunc_f32_e32 v76, v76
	v_mul_f32_e32 v8, 0x2f800000, v76
	v_floor_f32_e32 v8, v8
	v_fmac_f32_e32 v76, 0xcf800000, v8
	v_cvt_u32_f32_e32 v246, v76
	v_cvt_u32_f32_e32 v247, v8
	global_atomic_add_x2 v[236:237], v[246:247], off offset:1024
	s_nop 1
	v_mul_f32_e32 v60, 0x4f800000, v60
	v_trunc_f32_e32 v60, v60
	v_mul_f32_e32 v9, 0x2f800000, v60
	v_floor_f32_e32 v9, v9
	v_fmac_f32_e32 v60, 0xcf800000, v9
	v_cvt_u32_f32_e32 v246, v60
	v_cvt_u32_f32_e32 v247, v9
	global_atomic_add_x2 v[236:237], v[246:247], off offset:1152
	s_nop 1
	v_mul_f32_e32 v44, 0x4f800000, v44
	v_trunc_f32_e32 v44, v44
	v_mul_f32_e32 v10, 0x2f800000, v44
	v_floor_f32_e32 v10, v10
	v_fmac_f32_e32 v44, 0xcf800000, v10
	v_cvt_u32_f32_e32 v246, v44
	v_cvt_u32_f32_e32 v247, v10
	global_atomic_add_x2 v[236:237], v[246:247], off offset:1280
	s_nop 1
	v_mul_f32_e32 v28, 0x4f800000, v28
	v_trunc_f32_e32 v28, v28
	v_mul_f32_e32 v11, 0x2f800000, v28
	v_floor_f32_e32 v11, v11
	v_fmac_f32_e32 v28, 0xcf800000, v11
	v_cvt_u32_f32_e32 v246, v28
	v_cvt_u32_f32_e32 v247, v11
	global_atomic_add_x2 v[236:237], v[246:247], off offset:1408
	s_nop 1
